# attention: row-max chain moved into PV first-LDS-read shadow; next-step K fragment ds_reads hoisted above exps
# speedup vs baseline: 1.0001x; 1.0001x over previous
; #define SBAR() __builtin_amdgcn_sched_barrier(0)
; __device__ __forceinline__ int v_st(int k, int c) { const int kk = (k & ~0xC) | ((k & 4) << 1) | ((k & 8) >> 1); return ((kk >> 3) * 4 + (c >> 5)) * 512 + ((kk & 7) * 32 + (c & 31)) * 2; }
; __device__ __forceinline__ int v_rd_base(int lane) { return ((lane & 3) << 3) | (((lane >> 2) & 3) << 6) | (((lane >> 4) & 1) << 5) | (((lane >> 5) & 1) << 8); }
; #define SLOAD_A(k0) do { vs0a = *reinterpret_cast<const bf16x8*>(&Vh[(long)((k0) + sr) * LDK + sc]); vs1a = *reinterpret_cast<const bf16x8*>(&Vh[(long)((k0) + 32 + sr) * LDK + sc]); KLOAD(ks0a, ks1a, k0); } while (0)
; #define SLOAD_B(k0) do { vs0b = *reinterpret_cast<const bf16x8*>(&Vh[(long)((k0) + sr) * LDK + sc]); vs1b = *reinterpret_cast<const bf16x8*>(&Vh[(long)((k0) + 32 + sr) * LDK + sc]); KLOAD(ks0b, ks1b, k0); } while (0)
; #define SWRITE_A(b) do { *(bf16x8*)(V_lds + (b) * SHM_V + vst0) = vs0a; *(bf16x8*)(V_lds + (b) * SHM_V + vst1) = vs1a; KWRITE(b, ks0a, ks1a); } while (0)
; #define SWRITE_B(b) do { *(bf16x8*)(V_lds + (b) * SHM_V + vst0) = vs0b; *(bf16x8*)(V_lds + (b) * SHM_V + vst1) = vs1b; KWRITE(b, ks0b, ks1b); } while (0)
; template <int ND0, int LDQ, int LDK, int LDO> ...
;     ...
;   float m_reg = PRE ? 0.f : -1e30f, l_reg = 0; f32x16 o[4] = {}; bf16x8 qr[ND0];
;   const bf16_t* Qw = Qb + (long)(wid * QBLK + r32) * LDQ + hi * 8;
; #pragma unroll
;   for (int d0 = 0; d0 < ND0; ++d0) qr[d0] = *reinterpret_cast<const bf16x8*>(Qw + d0 * 16);
;   const int sr = tid >> 4, sc = (tid & 15) * 8, vst0 = v_st(sr, sc), vst1 = v_st(32 + sr, sc);
;   const int vb0 = (int)(uintptr_t)V_lds + v_rd_base(lane);
;   bf16x8 vs0a, vs1a, ks0a, ks1a = {}, vs0b, vs1b, ks0b, ks1b = {};
;   const int kr = tid >> 3, kcb = kofs + (tid & 7) * 16;
;     ...
;   f32x16 pA0, pA1, pB0, pB1; float mnA, mnB, alA, alB; bf16x8 pa0, pa1, pa2, pa3; const int NT = seq / KVBLK;
;   const char* Kq0 = K_lds + kofs; const char* Kq1 = K_lds + SHM_K + kofs;
;   if (ND0 == 4 && have_pf) { vs0a = pfv0; vs1a = pfv1; ks0a = pfk0; } else { SLOAD_A(0); }
;   asm volatile("s_waitcnt vmcnt(0)" ::: "memory"); SWRITE_A(0); __syncthreads();
;   qkt<ND0>(pA0, pA1, Kq0, qr, r32, hi); PSM(pA0, pA1, mnA, alA);
;   SLOAD_B(KVBLK); if (2 < NT) SLOAD_A(2 * KVBLK);
;   SWAIT(); SWRITE_B(1); __syncthreads();
;   for (int j = 1; j + 1 < NT; j += 2) {
;     SBAR(); qkt<ND0>(pB0, pB1, Kq1, qr, r32, hi);
.LBB0_145:
	v_and_b32_e32 v187, 63, v16
	v_and_b32_e32 v19, 0x3fffffc0, v16
	s_add_i32 s8, 0, 0x10000
	v_lshlrev_b32_e32 v20, 4, v187
	v_lshl_add_u32 v185, v19, 2, s8
	v_lshlrev_b32_e32 v19, 3, v187
	v_and_b32_e32 v20, 0xc0, v20
	v_lshlrev_b32_e32 v21, 1, v187
	v_and_or_b32 v20, v19, 24, v20
	v_and_b32_e32 v21, 32, v21
	v_and_b32_e32 v19, 0x100, v19
	v_or3_b32 v40, v20, v21, v19
	v_add_u32_e32 v19, 64, v17
	s_movk_i32 s41, 0x600
	v_mad_i64_i32 v[20:21], s[8:9], v19, s41, 0
	v_add_u32_e32 v19, 0x60, v17
	v_mad_i64_i32 v[24:25], s[8:9], v19, s41, 0
	v_add_u32_e32 v19, 0xa0, v17
	v_mad_i64_i32 v[36:37], s[8:9], v19, s41, 0
	v_add_u32_e32 v19, 0x80, v17
	v_or_b32_e32 v20, v20, v18
	v_or_b32_e32 v24, v24, v18
	v_mad_i64_i32 v[38:39], s[8:9], v19, s41, 0
	v_lshl_add_u64 v[28:29], v[20:21], 1, s[4:5]
	v_lshl_add_u64 v[32:33], v[24:25], 1, s[4:5]
	v_or_b32_e32 v36, v36, v18
	v_or_b32_e32 v38, v38, v18
	global_load_dwordx4 v[20:23], v[28:29], off offset:2560
	global_load_dwordx4 v[24:27], v[32:33], off offset:2560
	s_nop 0
	global_load_dwordx4 v[28:31], v[28:29], off offset:2048
	s_nop 0
	global_load_dwordx4 v[32:35], v[32:33], off offset:2048
	v_lshl_add_u64 v[36:37], v[36:37], 1, s[4:5]
	v_lshl_add_u64 v[18:19], v[38:39], 1, s[4:5]
	global_load_dwordx4 v[146:149], v[36:37], off offset:2048
	global_load_dwordx4 v[150:153], v[18:19], off offset:2048
	global_load_dwordx4 v[154:157], v[36:37], off offset:2560
	global_load_dwordx4 v[158:161], v[18:19], off offset:2560
	s_lshl_b32 s37, s37, 7
	s_cmp_lg_u32 0, -1
	s_cselect_b32 s40, 0, 0
	v_add_u32_e32 v194, s40, v40
	s_addk_i32 s40, 0x4000
	s_lshl_b64 s[4:5], s[34:35], 8
	s_add_u32 s4, s4, s17
	s_addc_u32 s5, s5, s16
	v_exp_f32_e32 v176, v0
	v_exp_f32_e32 v213, v1
	v_exp_f32_e32 v174, v2
	v_mov_b64_e32 v[0:1], s[4:5]
	s_movk_i32 s4, 0xc00
	v_and_b32_e32 v2, 15, v16
	v_exp_f32_e32 v177, v3
	v_exp_f32_e32 v173, v4
	v_exp_f32_e32 v175, v5
	v_exp_f32_e32 v171, v6
	v_exp_f32_e32 v172, v7
	v_exp_f32_e32 v167, v8
	v_exp_f32_e32 v169, v9
	v_exp_f32_e32 v166, v10
	v_exp_f32_e32 v168, v11
	v_exp_f32_e32 v163, v12
	v_exp_f32_e32 v165, v13
	v_exp_f32_e32 v162, v14
	v_exp_f32_e32 v164, v15
	v_mad_i64_i32 v[0:1], s[4:5], v17, s4, v[0:1]
	v_lshlrev_b32_e32 v2, 4, v2
	v_mov_b32_e32 v3, v113
	s_waitcnt vmcnt(4)
	v_lshl_add_u64 v[0:1], v[0:1], 0, v[2:3]
	v_mov_b32_e32 v14, v113
	v_mov_b32_e32 v15, v113
	v_add_u32_e32 v191, s40, v40
	v_lshl_add_u64 v[188:189], s[0:1], 0, v[0:1]
	v_mov_b32_e32 v0, v113
	v_mov_b32_e32 v1, v113
	v_mov_b32_e32 v2, v113
	v_mov_b32_e32 v4, v113
	v_mov_b32_e32 v5, v113
	v_mov_b32_e32 v6, v113
	v_mov_b32_e32 v7, v113
	v_mov_b32_e32 v8, v113
	v_mov_b32_e32 v9, v113
	v_mov_b32_e32 v10, v113
	v_mov_b32_e32 v11, v113
	v_mov_b32_e32 v12, v113
	v_mov_b32_e32 v13, v113
	v_mov_b64_e32 v[62:63], v[14:15]
	s_mov_b32 s39, 2
	s_waitcnt vmcnt(7)
	ds_write_b128 v197, v[20:23] offset:16384
	s_waitcnt vmcnt(6)
	ds_write_b128 v198, v[24:27] offset:16384
	s_waitcnt vmcnt(5)
	ds_write_b128 v195, v[28:31] offset:49152
	s_waitcnt vmcnt(4)
	ds_write_b128 v196, v[32:35] offset:49152
	v_mov_b64_e32 v[46:47], v[14:15]
	v_mov_b64_e32 v[30:31], v[14:15]
	v_cmp_gt_u32_e64 s[8:9], 32, v187
	v_lshl_add_u32 v190, v179, 2, v185
	v_mov_b32_e32 v192, 0
	v_mov_b64_e32 v[60:61], v[12:13]
	v_mov_b64_e32 v[58:59], v[10:11]
	v_mov_b64_e32 v[56:57], v[8:9]
	v_mov_b64_e32 v[54:55], v[6:7]
	v_mov_b64_e32 v[52:53], v[4:5]
	v_mov_b64_e32 v[50:51], v[2:3]
	v_mov_b64_e32 v[48:49], v[0:1]
	v_mov_b64_e32 v[44:45], v[12:13]
	v_mov_b64_e32 v[42:43], v[10:11]
	v_mov_b64_e32 v[40:41], v[8:9]
	v_mov_b64_e32 v[38:39], v[6:7]
	v_mov_b64_e32 v[36:37], v[4:5]
	v_mov_b64_e32 v[34:35], v[2:3]
	v_mov_b64_e32 v[32:33], v[0:1]
	v_mov_b64_e32 v[28:29], v[12:13]
	v_mov_b64_e32 v[26:27], v[10:11]
	v_mov_b64_e32 v[24:25], v[8:9]
	v_mov_b64_e32 v[22:23], v[6:7]
	v_mov_b64_e32 v[20:21], v[4:5]
	v_mov_b64_e32 v[18:19], v[2:3]
	v_mov_b64_e32 v[16:17], v[0:1]
	s_waitcnt lgkmcnt(0)
	s_barrier
	ds_read_b128 v[80:83], v199 offset:49152
	ds_read_b128 v[84:87], v199 offset:57344
.LBB0_146:
	ds_read_b128 v[208:211], v200 offset:49152
	ds_read_b128 v[214:217], v200 offset:57344
	v_exp_f32_e32 v170, v64
	v_add_f32_e32 v64, 0, v176
	s_waitcnt lgkmcnt(3)
	v_mfma_f32_32x32x16_bf16 v[96:111], v[80:83], v[114:117], 0
	v_add_f32_e32 v64, v213, v64
	v_add_f32_e32 v64, v174, v64
	v_add_f32_e32 v64, v177, v64
	v_add_f32_e32 v64, v173, v64
	v_add_f32_e32 v64, v175, v64
	v_add_f32_e32 v64, v171, v64
	v_add_f32_e32 v64, v172, v64
	s_waitcnt lgkmcnt(2)
	v_mfma_f32_32x32x16_bf16 v[80:95], v[84:87], v[114:117], 0
	v_add_f32_e32 v64, v167, v64
	v_add_f32_e32 v64, v169, v64
	v_add_f32_e32 v64, v166, v64
	v_add_f32_e32 v64, v168, v64
	v_add_f32_e32 v64, v163, v64
	v_add_f32_e32 v64, v165, v64
	v_add_f32_e32 v64, v162, v64
	s_waitcnt lgkmcnt(1)
	v_mfma_f32_32x32x16_bf16 v[96:111], v[208:211], v[122:125], v[96:111]
	v_exp_f32_e32 v212, v67
	v_add_f32_e32 v64, v164, v64
	v_add_f32_e32 v64, v170, v64
	v_exp_f32_e32 v218, v72
	v_exp_f32_e32 v219, v73
	v_exp_f32_e32 v220, v74
	v_exp_f32_e32 v221, v75
	s_waitcnt lgkmcnt(0)
	v_mfma_f32_32x32x16_bf16 v[80:95], v[214:217], v[122:125], v[80:95]
	ds_read_b128 v[208:211], v202 offset:49152
	ds_read_b128 v[214:217], v202 offset:57344
	v_exp_f32_e32 v222, v76
	v_exp_f32_e32 v223, v77
	v_exp_f32_e32 v224, v78
	v_exp_f32_e32 v79, v79
	s_waitcnt lgkmcnt(1)
	v_mfma_f32_32x32x16_bf16 v[96:111], v[208:211], v[142:145], v[96:111]
	s_waitcnt lgkmcnt(0)
	v_mfma_f32_32x32x16_bf16 v[80:95], v[214:217], v[142:145], v[80:95]
	ds_read_b128 v[208:211], v201 offset:49152
	ds_read_b128 v[214:217], v201 offset:57344
	s_waitcnt lgkmcnt(1)
; #define SBAR() __builtin_amdgcn_sched_barrier(0)
; #define SLOAD_B(k0) do { vs0b = *reinterpret_cast<const bf16x8*>(&Vh[(long)((k0) + sr) * LDK + sc]); vs1b = *reinterpret_cast<const bf16x8*>(&Vh[(long)((k0) + 32 + sr) * LDK + sc]); KLOAD(ks0b, ks1b, k0); } while (0)
; __device__ __forceinline__ void finishSM(f32x16& p0, f32x16& p1, float alpha, float& l_reg, bf16x8& pa0, bf16x8& pa1, bf16x8& pa2, bf16x8& pa3) {
; #pragma unroll
;   for (int r = 0; r < 16; ++r) p1[r] = __builtin_amdgcn_exp2f(p1[r]);
;   float ps = 0;
; #pragma unroll
;   for (int r = 0; r < 16; ++r) ps += p0[r];
; #pragma unroll
;   for (int r = 0; r < 16; ++r) ps += p1[r];
;   { auto rr = __builtin_amdgcn_permlane32_swap(__float_as_uint(ps), __float_as_uint(ps), false, false);
;     ps = __uint_as_float(rr[0]) + __uint_as_float(rr[1]); }
;   l_reg = l_reg * alpha + ps;
;     ...
;   PK4(p0, 0, pa0); PK4(p0, 8, pa1); PK4(p1, 0, pa2); PK4(p1, 8, pa3);
; template <int ND0, int LDQ, int LDK, int LDO> ...
;     ...
;     SBAR(); qkt<ND0>(pB0, pB1, Kq1, qr, r32, hi);
;     finishSM(pA0, pA1, alA, l_reg, pa0, pa1, pa2, pa3); SBAR();
;     SLOAD_B((j + 2) * KVBLK); SBAR();
	v_mfma_f32_32x32x16_bf16 v[96:111], v[208:211], v[138:141], v[96:111]
	s_waitcnt lgkmcnt(0)
	v_mfma_f32_32x32x16_bf16 v[80:95], v[214:217], v[138:141], v[80:95]
	ds_read_b128 v[208:211], v203 offset:49152
	ds_read_b128 v[214:217], v203 offset:57344
	s_waitcnt lgkmcnt(1)
	v_mfma_f32_32x32x16_bf16 v[96:111], v[208:211], v[134:137], v[96:111]
	s_waitcnt lgkmcnt(0)
	v_mfma_f32_32x32x16_bf16 v[80:95], v[214:217], v[134:137], v[80:95]
	ds_read_b128 v[208:211], v204 offset:49152
	ds_read_b128 v[214:217], v204 offset:57344
	s_waitcnt lgkmcnt(1)
	v_mfma_f32_32x32x16_bf16 v[96:111], v[208:211], v[130:133], v[96:111]
	s_waitcnt lgkmcnt(0)
	v_mfma_f32_32x32x16_bf16 v[80:95], v[214:217], v[130:133], v[80:95]
	ds_read_b128 v[208:211], v206 offset:49152
	ds_read_b128 v[214:217], v206 offset:57344
	s_waitcnt lgkmcnt(1)
	v_mfma_f32_32x32x16_bf16 v[96:111], v[208:211], v[126:129], v[96:111]
	s_waitcnt lgkmcnt(0)
	v_mfma_f32_32x32x16_bf16 v[80:95], v[214:217], v[126:129], v[80:95]
	ds_read_b128 v[208:211], v205 offset:49152
	ds_read_b128 v[214:217], v205 offset:57344
	s_waitcnt lgkmcnt(1)
	v_mfma_f32_32x32x16_bf16 v[96:111], v[208:211], v[118:121], v[96:111]
	v_exp_f32_e32 v210, v65
	v_exp_f32_e32 v211, v66
	v_add_f32_e32 v64, v210, v64
	v_add_f32_e32 v64, v211, v64
	v_add_f32_e32 v64, v212, v64
	s_waitcnt lgkmcnt(0)
	v_mfma_f32_32x32x16_bf16 v[80:95], v[214:217], v[118:121], v[80:95]
	v_exp_f32_e32 v214, v68
	v_exp_f32_e32 v215, v69
	v_exp_f32_e32 v216, v70
	v_exp_f32_e32 v217, v71
	v_add_f32_e32 v64, v214, v64
	v_add_f32_e32 v64, v215, v64
	v_add_f32_e32 v64, v216, v64
	v_add_f32_e32 v64, v217, v64
	v_add_f32_e32 v64, v218, v64
	v_add_f32_e32 v64, v219, v64
	v_add_f32_e32 v64, v220, v64
	v_add_f32_e32 v64, v221, v64
	v_add_f32_e32 v64, v222, v64
	v_add_f32_e32 v64, v223, v64
	v_add_f32_e32 v64, v224, v64
	v_add_f32_e32 v208, v79, v64
	v_mov_b32_e32 v209, v208
	s_nop 1
	v_permlane32_swap_b32_e32 v208, v209
	v_cvt_pk_bf16_f32 v64, v176, v213
	v_cvt_pk_bf16_f32 v65, v174, v177
	v_cvt_pk_bf16_f32 v66, v173, v175
	v_cvt_pk_bf16_f32 v67, v171, v172
	v_cvt_pk_bf16_f32 v68, v167, v169
	v_cvt_pk_bf16_f32 v69, v166, v168
	v_cvt_pk_bf16_f32 v70, v163, v165
	v_cvt_pk_bf16_f32 v71, v162, v164
	v_cvt_pk_bf16_f32 v72, v170, v210
	v_cvt_pk_bf16_f32 v73, v211, v212
	v_cvt_pk_bf16_f32 v74, v214, v215
	v_cvt_pk_bf16_f32 v75, v216, v217
	v_cvt_pk_bf16_f32 v76, v218, v219
	v_cvt_pk_bf16_f32 v77, v220, v221
	v_cvt_pk_bf16_f32 v78, v222, v223
	v_cvt_pk_bf16_f32 v79, v224, v79
	s_nop 0
	v_permlane32_swap_b32_e32 v64, v66
	v_permlane32_swap_b32_e32 v65, v67
	v_permlane32_swap_b32_e32 v68, v70
	v_permlane32_swap_b32_e32 v69, v71
	v_permlane32_swap_b32_e32 v72, v74
	v_permlane32_swap_b32_e32 v73, v75
	v_permlane32_swap_b32_e32 v76, v78
	v_permlane32_swap_b32_e32 v77, v79
	s_mov_b32 s4, 0xfffb8000
	v_add_co_u32_e32 v166, vcc, s4, v188
	s_mov_b32 s4, 0xfffd0000
	s_nop 0
	v_addc_co_u32_e32 v167, vcc, -1, v189, vcc
	v_add_co_u32_e32 v174, vcc, s4, v188
	s_nop 1
	v_addc_co_u32_e32 v175, vcc, -1, v189, vcc
	global_load_dwordx4 v[162:165], v[166:167], off
	global_load_dwordx4 v[170:173], v[166:167], off offset:-512
	s_nop 0
	global_load_dwordx4 v[166:169], v[174:175], off
	s_nop 0
	global_load_dwordx4 v[174:177], v[174:175], off offset:-512
	v_cmp_neq_f32_e32 vcc, 0, v193
	ds_read_b64_tr_b16 v[210:211], v194 offset:0
	ds_read_b64_tr_b16 v[212:213], v194 offset:0x800
	ds_read_b64_tr_b16 v[214:215], v194 offset:0x1000
	ds_read_b64_tr_b16 v[216:217], v194 offset:0x1800
	ds_read_b64_tr_b16 v[218:219], v194 offset:0x2000
	ds_read_b64_tr_b16 v[220:221], v194 offset:0x2800
	ds_read_b64_tr_b16 v[222:223], v194 offset:0x3000
	ds_read_b64_tr_b16 v[224:225], v194 offset:0x3800
	s_cbranch_vccnz .LBB0_163
; #define SBAR() __builtin_amdgcn_sched_barrier(0)
; __device__ __forceinline__ void partialSM_pre(f32x16& p0, f32x16& p1, float& m_ref, float& alpha, const float thr2) {
;     ...
;   float pmax = p0[0];
; #pragma unroll
;   for (int r = 1; r < 16; ++r) pmax = fmaxf(pmax, p0[r]);
; #pragma unroll
;   for (int r = 0; r < 16; ++r) pmax = fmaxf(pmax, p1[r]);
;   { auto rr = __builtin_amdgcn_permlane32_swap(__float_as_uint(pmax), __float_as_uint(pmax), false, false);
;     pmax = fmaxf(__uint_as_float(rr[0]), __uint_as_float(rr[1])); }
;   if (__builtin_expect(__all(pmax <= thr2), 1)) { alpha = 1.f; }
; template <int OFF> __device__ __forceinline__ s16x4 tr_read(int vb) {
;   s16x4 r; asm volatile("ds_read_b64_tr_b16 %0, %1 offset:%2" : "=&v"(r) : "v"(vb), "i"(OFF) : "memory"); return r;
; }
; template <int D0> __device__ __forceinline__ void pv_one(f32x16& od, int vb, bf16x8 pa0, bf16x8 pa1, bf16x8 pa2, bf16x8 pa3) {
;   const s16x4 l0 = tr_read<v_rd_off(D0, 0, 0)>(vb), h0 = tr_read<v_rd_off(D0, 0, 1)>(vb), l1 = tr_read<v_rd_off(D0, 1, 0)>(vb), h1 = tr_read<v_rd_off(D0, 1, 1)>(vb);
;   const s16x4 l2 = tr_read<v_rd_off(D0, 2, 0)>(vb), h2 = tr_read<v_rd_off(D0, 2, 1)>(vb), l3 = tr_read<v_rd_off(D0, 3, 0)>(vb), h3 = tr_read<v_rd_off(D0, 3, 1)>(vb);
;   asm volatile("s_waitcnt lgkmcnt(0)" ::: "memory"); SBAR();
;     ...
;   od = __builtin_amdgcn_mfma_f32_32x32x16_bf16(pa0, PK(l0, h0), od, 0, 0, 0);
;   od = __builtin_amdgcn_mfma_f32_32x32x16_bf16(pa1, PK(l1, h1), od, 0, 0, 0);
;   od = __builtin_amdgcn_mfma_f32_32x32x16_bf16(pa2, PK(l2, h2), od, 0, 0, 0);
;   od = __builtin_amdgcn_mfma_f32_32x32x16_bf16(pa3, PK(l3, h3), od, 0, 0, 0);
;     ...
; }
; __device__ __forceinline__ void pv_d0(f32x16* o, int vb, bf16x8 pa0, bf16x8 pa1, bf16x8 pa2, bf16x8 pa3) {
;   pv_one<0>(o[0], vb, pa0, pa1, pa2, pa3); pv_one<1>(o[1], vb, pa0, pa1, pa2, pa3); pv_one<2>(o[2], vb, pa0, pa1, pa2, pa3); pv_one<3>(o[3], vb, pa0, pa1, pa2, pa3);
.LBB0_147:
	v_max_f32_e32 v180, v97, v97
	v_max_f32_e32 v182, v96, v96
	v_max_f32_e32 v180, v182, v180
	v_max3_f32 v180, v180, v98, v99
	v_max3_f32 v180, v180, v100, v101
	v_max3_f32 v180, v180, v102, v103
	v_max3_f32 v180, v180, v104, v105
	v_max3_f32 v180, v180, v106, v107
	v_max3_f32 v180, v180, v108, v109
	v_max3_f32 v180, v180, v110, v111
	v_max3_f32 v180, v180, v80, v81
	v_max3_f32 v180, v180, v82, v83
	v_max3_f32 v180, v180, v84, v85
	v_max3_f32 v180, v180, v86, v87
	v_max3_f32 v180, v180, v88, v89
	v_max3_f32 v180, v180, v90, v91
	v_max3_f32 v180, v180, v92, v93
	v_max3_f32 v180, v180, v94, v95
	v_mov_b32_e32 v182, v180
	s_nop 1
	v_permlane32_swap_b32_e32 v180, v182
	v_max_f32_e32 v182, v182, v182
	v_max_f32_e32 v180, v180, v180
	v_max_f32_e32 v180, v180, v182
	s_waitcnt lgkmcnt(0)
	s_nop 0
	v_mfma_f32_32x32x16_bf16 v[0:15], v[64:67], v[210:213], v[0:15]
	ds_read_b64_tr_b16 v[210:211], v194 offset:0x200
	ds_read_b64_tr_b16 v[212:213], v194 offset:0xa00
	v_mfma_f32_32x32x16_bf16 v[0:15], v[68:71], v[214:217], v[0:15]
	ds_read_b64_tr_b16 v[214:215], v194 offset:0x1200
	ds_read_b64_tr_b16 v[216:217], v194 offset:0x1a00
	v_mfma_f32_32x32x16_bf16 v[0:15], v[72:75], v[218:221], v[0:15]
	ds_read_b64_tr_b16 v[218:219], v194 offset:0x2200
	ds_read_b64_tr_b16 v[220:221], v194 offset:0x2a00
	v_mfma_f32_32x32x16_bf16 v[0:15], v[76:79], v[222:225], v[0:15]
	ds_read_b64_tr_b16 v[222:223], v194 offset:0x3200
	ds_read_b64_tr_b16 v[224:225], v194 offset:0x3a00
	s_waitcnt lgkmcnt(0)
	v_mfma_f32_32x32x16_bf16 v[48:63], v[64:67], v[210:213], v[48:63]
	ds_read_b64_tr_b16 v[210:211], v194 offset:0x400
	ds_read_b64_tr_b16 v[212:213], v194 offset:0xc00
	v_mfma_f32_32x32x16_bf16 v[48:63], v[68:71], v[214:217], v[48:63]
	ds_read_b64_tr_b16 v[214:215], v194 offset:0x1400
	ds_read_b64_tr_b16 v[216:217], v194 offset:0x1c00
	v_mfma_f32_32x32x16_bf16 v[48:63], v[72:75], v[218:221], v[48:63]
	ds_read_b64_tr_b16 v[218:219], v194 offset:0x2400
	ds_read_b64_tr_b16 v[220:221], v194 offset:0x2c00
	v_mfma_f32_32x32x16_bf16 v[48:63], v[76:79], v[222:225], v[48:63]
	ds_read_b64_tr_b16 v[222:223], v194 offset:0x3400
	ds_read_b64_tr_b16 v[224:225], v194 offset:0x3c00
	s_waitcnt lgkmcnt(0)
	v_mfma_f32_32x32x16_bf16 v[32:47], v[64:67], v[210:213], v[32:47]
	ds_read_b64_tr_b16 v[210:211], v194 offset:0x600
	ds_read_b64_tr_b16 v[212:213], v194 offset:0xe00
	v_mfma_f32_32x32x16_bf16 v[32:47], v[68:71], v[214:217], v[32:47]
	ds_read_b64_tr_b16 v[214:215], v194 offset:0x1600
	ds_read_b64_tr_b16 v[216:217], v194 offset:0x1e00
	v_mfma_f32_32x32x16_bf16 v[32:47], v[72:75], v[218:221], v[32:47]
	ds_read_b64_tr_b16 v[218:219], v194 offset:0x2600
	ds_read_b64_tr_b16 v[220:221], v194 offset:0x2e00
	v_mfma_f32_32x32x16_bf16 v[32:47], v[76:79], v[222:225], v[32:47]
	ds_read_b64_tr_b16 v[222:223], v194 offset:0x3600
	ds_read_b64_tr_b16 v[224:225], v194 offset:0x3e00
	s_waitcnt lgkmcnt(0)
	v_mfma_f32_32x32x16_bf16 v[16:31], v[64:67], v[210:213], v[16:31]
	s_waitcnt vmcnt(4)
	ds_write_b128 v195, v[150:153] offset:32768
	ds_write_b128 v196, v[146:149] offset:32768
	v_mfma_f32_32x32x16_bf16 v[16:31], v[68:71], v[214:217], v[16:31]
	v_mfma_f32_32x32x16_bf16 v[16:31], v[72:75], v[218:221], v[16:31]
	v_mfma_f32_32x32x16_bf16 v[16:31], v[76:79], v[222:225], v[16:31]
	v_cmp_ge_f32_e32 vcc, s45, v180
	s_cmp_eq_u64 vcc, exec
	v_mov_b32_e32 v210, 1.0
	s_cbranch_scc0 .LBB0_164

; #define SBAR() __builtin_amdgcn_sched_barrier(0)
; #define SLOAD_A(k0) do { vs0a = *reinterpret_cast<const bf16x8*>(&Vh[(long)((k0) + sr) * LDK + sc]); vs1a = *reinterpret_cast<const bf16x8*>(&Vh[(long)((k0) + 32 + sr) * LDK + sc]); KLOAD(ks0a, ks1a, k0); } while (0)
; __device__ __forceinline__ void finishSM(f32x16& p0, f32x16& p1, float alpha, float& l_reg, bf16x8& pa0, bf16x8& pa1, bf16x8& pa2, bf16x8& pa3) {
; #pragma unroll
;   for (int r = 0; r < 16; ++r) p1[r] = __builtin_amdgcn_exp2f(p1[r]);
;   float ps = 0;
; #pragma unroll
;   for (int r = 0; r < 16; ++r) ps += p0[r];
; #pragma unroll
;   for (int r = 0; r < 16; ++r) ps += p1[r];
;   { auto rr = __builtin_amdgcn_permlane32_swap(__float_as_uint(ps), __float_as_uint(ps), false, false);
;     ps = __uint_as_float(rr[0]) + __uint_as_float(rr[1]); }
;   l_reg = l_reg * alpha + ps;
;     ...
;   PK4(p0, 0, pa0); PK4(p0, 8, pa1); PK4(p1, 0, pa2); PK4(p1, 8, pa3);
; template <int ND0, int LDQ, int LDK, int LDO> ...
;     ...
;     SBAR(); qkt<ND0>(pA0, pA1, Kq0, qr, r32, hi);
;     finishSM(pB0, pB1, alB, l_reg, pa0, pa1, pa2, pa3); SBAR();
;     if (j + 3 < NT) SLOAD_A((j + 3) * KVBLK); SBAR();
.LBB0_153:
	v_mov_b32_e32 v242, 0x800
	ds_read_b128 v[64:67], v199 offset:32768
	ds_read_b128 v[68:71], v199 offset:40960
	ds_read_b128 v[238:241], v200 offset:32768
	ds_read_b128 v[234:237], v200 offset:40960
	v_exp_f32_e32 v226, v96
	v_exp_f32_e32 v244, v97
	v_exp_f32_e32 v224, v98
	v_exp_f32_e32 v227, v99
	v_exp_f32_e32 v223, v100
	v_exp_f32_e32 v225, v101
	v_exp_f32_e32 v221, v102
	v_exp_f32_e32 v222, v103
	v_exp_f32_e32 v218, v104
	v_exp_f32_e32 v220, v105
	v_exp_f32_e32 v217, v106
	v_exp_f32_e32 v219, v107
	v_exp_f32_e32 v214, v108
	v_exp_f32_e32 v216, v109
	v_exp_f32_e32 v213, v110
	v_exp_f32_e32 v215, v111
	v_exp_f32_e32 v245, v88
	v_exp_f32_e32 v246, v89
	s_waitcnt lgkmcnt(3)
	v_mfma_f32_32x32x16_bf16 v[96:111], v[64:67], v[114:117], 0
	v_exp_f32_e32 v247, v90
	v_exp_f32_e32 v231, v91
	v_exp_f32_e32 v243, v92
	v_exp_f32_e32 v252, v93
	v_exp_f32_e32 v253, v94
	v_exp_f32_e32 v95, v95
	s_waitcnt lgkmcnt(2)
	v_mfma_f32_32x32x16_bf16 v[64:79], v[68:71], v[114:117], 0
	s_waitcnt lgkmcnt(1)
	v_mfma_f32_32x32x16_bf16 v[96:111], v[238:241], v[122:125], v[96:111]
	s_waitcnt lgkmcnt(0)
	v_mfma_f32_32x32x16_bf16 v[64:79], v[234:237], v[122:125], v[64:79]
	ds_read_b128 v[234:237], v202 offset:32768
	ds_read_b128 v[238:241], v202 offset:40960
	s_waitcnt lgkmcnt(1)
	v_mfma_f32_32x32x16_bf16 v[96:111], v[234:237], v[142:145], v[96:111]
	s_waitcnt lgkmcnt(0)
	v_mfma_f32_32x32x16_bf16 v[64:79], v[238:241], v[142:145], v[64:79]
	ds_read_b128 v[234:237], v201 offset:32768
	ds_read_b128 v[238:241], v201 offset:40960
	s_waitcnt lgkmcnt(1)
	v_mfma_f32_32x32x16_bf16 v[96:111], v[234:237], v[138:141], v[96:111]
	s_waitcnt lgkmcnt(0)
	v_mfma_f32_32x32x16_bf16 v[64:79], v[238:241], v[138:141], v[64:79]
	ds_read_b128 v[234:237], v203 offset:32768
	ds_read_b128 v[238:241], v203 offset:40960
	s_waitcnt lgkmcnt(1)
	v_mfma_f32_32x32x16_bf16 v[96:111], v[234:237], v[134:137], v[96:111]
	s_waitcnt lgkmcnt(0)
	v_mfma_f32_32x32x16_bf16 v[64:79], v[238:241], v[134:137], v[64:79]
	ds_read_b128 v[234:237], v204 offset:32768
	ds_read_b128 v[238:241], v204 offset:40960
	s_waitcnt lgkmcnt(1)
	v_mfma_f32_32x32x16_bf16 v[96:111], v[234:237], v[130:133], v[96:111]
	s_waitcnt lgkmcnt(0)
	v_mfma_f32_32x32x16_bf16 v[64:79], v[238:241], v[130:133], v[64:79]
	ds_read_b128 v[234:237], v206 offset:32768
	ds_read_b128 v[238:241], v206 offset:40960
	s_waitcnt lgkmcnt(1)
	v_mfma_f32_32x32x16_bf16 v[96:111], v[234:237], v[126:129], v[96:111]
	s_waitcnt lgkmcnt(0)
	v_mfma_f32_32x32x16_bf16 v[64:79], v[238:241], v[126:129], v[64:79]
	ds_read_b128 v[234:237], v205 offset:32768
	ds_read_b128 v[238:241], v205 offset:40960
	s_waitcnt lgkmcnt(1)
	v_mfma_f32_32x32x16_bf16 v[96:111], v[234:237], v[118:121], v[96:111]
	v_exp_f32_e32 v234, v80
	v_add_f32_e32 v80, 0, v226
	v_add_f32_e32 v80, v244, v80
	v_add_f32_e32 v80, v224, v80
	v_add_f32_e32 v80, v227, v80
	v_add_f32_e32 v80, v223, v80
	v_add_f32_e32 v80, v225, v80
	v_add_f32_e32 v80, v221, v80
	v_add_f32_e32 v80, v222, v80
	v_add_f32_e32 v80, v218, v80
	v_add_f32_e32 v80, v220, v80
	v_add_f32_e32 v80, v217, v80
	v_add_f32_e32 v80, v219, v80
	v_add_f32_e32 v80, v214, v80
	v_exp_f32_e32 v235, v81
	v_add_f32_e32 v80, v216, v80
	v_exp_f32_e32 v236, v82
	v_add_f32_e32 v80, v213, v80
	v_exp_f32_e32 v237, v83
	v_add_f32_e32 v80, v215, v80
	s_waitcnt lgkmcnt(0)
	v_mfma_f32_32x32x16_bf16 v[64:79], v[238:241], v[118:121], v[64:79]
	v_exp_f32_e32 v238, v84
	v_add_f32_e32 v80, v234, v80
	v_exp_f32_e32 v239, v85
	v_add_f32_e32 v80, v235, v80
	v_exp_f32_e32 v240, v86
	v_add_f32_e32 v80, v236, v80
	v_exp_f32_e32 v241, v87
	v_add_f32_e32 v80, v237, v80
	v_add_f32_e32 v80, v238, v80
	v_add_f32_e32 v80, v239, v80
	v_add_f32_e32 v80, v240, v80
	v_add_f32_e32 v80, v241, v80
	v_add_f32_e32 v80, v245, v80
	v_add_f32_e32 v80, v246, v80
	v_add_f32_e32 v80, v247, v80
	v_add_f32_e32 v80, v231, v80
	v_add_f32_e32 v80, v243, v80
	v_add_f32_e32 v80, v252, v80
	v_add_f32_e32 v80, v253, v80
	v_add_f32_e32 v211, v95, v80
	v_mov_b32_e32 v212, v211
	v_cvt_pk_bf16_f32 v80, v226, v244
	v_cvt_pk_bf16_f32 v81, v224, v227
	v_cvt_pk_bf16_f32 v82, v223, v225
	v_cvt_pk_bf16_f32 v83, v221, v222
	v_cvt_pk_bf16_f32 v84, v218, v220
	v_cvt_pk_bf16_f32 v85, v217, v219
	v_cvt_pk_bf16_f32 v86, v214, v216
	v_cvt_pk_bf16_f32 v87, v213, v215
	v_cvt_pk_bf16_f32 v88, v234, v235
	v_cvt_pk_bf16_f32 v89, v236, v237
	v_cvt_pk_bf16_f32 v90, v238, v239
	v_cvt_pk_bf16_f32 v91, v240, v241
	v_cvt_pk_bf16_f32 v92, v245, v246
	v_cvt_pk_bf16_f32 v93, v247, v231
	v_cvt_pk_bf16_f32 v94, v243, v252
	v_cvt_pk_bf16_f32 v95, v253, v95
	s_nop 1
	v_permlane32_swap_b32_e32 v211, v212
	v_permlane32_swap_b32_e32 v80, v82
	v_permlane32_swap_b32_e32 v81, v83
	v_permlane32_swap_b32_e32 v84, v86
	v_permlane32_swap_b32_e32 v85, v87
	v_permlane32_swap_b32_e32 v88, v90
	v_permlane32_swap_b32_e32 v89, v91
	v_permlane32_swap_b32_e32 v92, v94
	v_permlane32_swap_b32_e32 v93, v95
	s_add_i32 s39, s39, 2
	s_cmp_ge_u32 s39, s38
	s_cselect_b64 s[4:5], -1, 0
	s_and_b64 vcc, exec, s[4:5]
	s_cbranch_vccnz .Lgqa_pf_skip
	v_add_co_u32_e32 v146, vcc, 0xfffe8000, v188
	s_nop 1
	v_addc_co_u32_e32 v147, vcc, -1, v189, vcc
	global_load_dwordx4 v[158:161], v[146:147], off
	global_load_dwordx4 v[150:153], v[146:147], off offset:-512
	global_load_dwordx4 v[154:157], v[188:189], off
	s_nop 0
	global_load_dwordx4 v[146:149], v[188:189], off offset:-512
; #define SBAR() __builtin_amdgcn_sched_barrier(0)
; __device__ __forceinline__ void partialSM_pre(f32x16& p0, f32x16& p1, float& m_ref, float& alpha, const float thr2) {
;     ...
;   float pmax = p0[0];
; #pragma unroll
;   for (int r = 1; r < 16; ++r) pmax = fmaxf(pmax, p0[r]);
; #pragma unroll
;   for (int r = 0; r < 16; ++r) pmax = fmaxf(pmax, p1[r]);
;   { auto rr = __builtin_amdgcn_permlane32_swap(__float_as_uint(pmax), __float_as_uint(pmax), false, false);
;     pmax = fmaxf(__uint_as_float(rr[0]), __uint_as_float(rr[1])); }
;   if (__builtin_expect(__all(pmax <= thr2), 1)) { alpha = 1.f; }
; template <int OFF> __device__ __forceinline__ s16x4 tr_read(int vb) {
;   s16x4 r; asm volatile("ds_read_b64_tr_b16 %0, %1 offset:%2" : "=&v"(r) : "v"(vb), "i"(OFF) : "memory"); return r;
; }
; template <int D0> __device__ __forceinline__ void pv_one(f32x16& od, int vb, bf16x8 pa0, bf16x8 pa1, bf16x8 pa2, bf16x8 pa3) {
;   const s16x4 l0 = tr_read<v_rd_off(D0, 0, 0)>(vb), h0 = tr_read<v_rd_off(D0, 0, 1)>(vb), l1 = tr_read<v_rd_off(D0, 1, 0)>(vb), h1 = tr_read<v_rd_off(D0, 1, 1)>(vb);
;   const s16x4 l2 = tr_read<v_rd_off(D0, 2, 0)>(vb), h2 = tr_read<v_rd_off(D0, 2, 1)>(vb), l3 = tr_read<v_rd_off(D0, 3, 0)>(vb), h3 = tr_read<v_rd_off(D0, 3, 1)>(vb);
;   asm volatile("s_waitcnt lgkmcnt(0)" ::: "memory"); SBAR();
;     ...
;   od = __builtin_amdgcn_mfma_f32_32x32x16_bf16(pa0, PK(l0, h0), od, 0, 0, 0);
;   od = __builtin_amdgcn_mfma_f32_32x32x16_bf16(pa1, PK(l1, h1), od, 0, 0, 0);
;   od = __builtin_amdgcn_mfma_f32_32x32x16_bf16(pa2, PK(l2, h2), od, 0, 0, 0);
;   od = __builtin_amdgcn_mfma_f32_32x32x16_bf16(pa3, PK(l3, h3), od, 0, 0, 0);
;     ...
; }
; __device__ __forceinline__ void pv_d0(f32x16* o, int vb, bf16x8 pa0, bf16x8 pa1, bf16x8 pa2, bf16x8 pa3) {
;   pv_one<0>(o[0], vb, pa0, pa1, pa2, pa3); pv_one<1>(o[1], vb, pa0, pa1, pa2, pa3); pv_one<2>(o[2], vb, pa0, pa1, pa2, pa3); pv_one<3>(o[3], vb, pa0, pa1, pa2, pa3);
.LBB0_155:
	v_cmp_neq_f32_e32 vcc, 0, v193
	ds_read_b64_tr_b16 v[214:215], v191 offset:0
	ds_read_b64_tr_b16 v[216:217], v191 offset:0x800
	ds_read_b64_tr_b16 v[218:219], v191 offset:0x1000
	ds_read_b64_tr_b16 v[220:221], v191 offset:0x1800
	ds_read_b64_tr_b16 v[222:223], v191 offset:0x2000
	ds_read_b64_tr_b16 v[224:225], v191 offset:0x2800
	ds_read_b64_tr_b16 v[234:235], v191 offset:0x3000
	ds_read_b64_tr_b16 v[236:237], v191 offset:0x3800
	s_cbranch_vccnz .LBB0_165
.LBB0_156:
	v_max_f32_e32 v180, v97, v97
	v_max_f32_e32 v182, v96, v96
	v_max_f32_e32 v180, v182, v180
	v_max3_f32 v180, v180, v98, v99
	v_max3_f32 v180, v180, v100, v101
	v_max3_f32 v180, v180, v102, v103
	v_max3_f32 v180, v180, v104, v105
	v_max3_f32 v180, v180, v106, v107
	v_max3_f32 v180, v180, v108, v109
	v_max3_f32 v180, v180, v110, v111
	v_max3_f32 v180, v180, v64, v65
	v_max3_f32 v180, v180, v66, v67
	v_max3_f32 v180, v180, v68, v69
	v_max3_f32 v180, v180, v70, v71
	v_max3_f32 v180, v180, v72, v73
	v_max3_f32 v180, v180, v74, v75
	v_max3_f32 v180, v180, v76, v77
	v_max3_f32 v180, v180, v78, v79
	v_mov_b32_e32 v182, v180
	s_nop 1
	v_permlane32_swap_b32_e32 v180, v182
	v_max_f32_e32 v182, v182, v182
	v_max_f32_e32 v180, v180, v180
	v_max_f32_e32 v180, v180, v182
	s_waitcnt lgkmcnt(0)
	s_nop 0
	v_mfma_f32_32x32x16_bf16 v[0:15], v[80:83], v[214:217], v[0:15]
	ds_read_b64_tr_b16 v[214:215], v191 offset:0x200
	ds_read_b64_tr_b16 v[216:217], v191 offset:0xa00
	v_mfma_f32_32x32x16_bf16 v[0:15], v[84:87], v[218:221], v[0:15]
	ds_read_b64_tr_b16 v[218:219], v191 offset:0x1200
	ds_read_b64_tr_b16 v[220:221], v191 offset:0x1a00
	v_mfma_f32_32x32x16_bf16 v[0:15], v[88:91], v[222:225], v[0:15]
	ds_read_b64_tr_b16 v[222:223], v191 offset:0x2200
	ds_read_b64_tr_b16 v[224:225], v191 offset:0x2a00
	v_mfma_f32_32x32x16_bf16 v[0:15], v[92:95], v[234:237], v[0:15]
	ds_read_b64_tr_b16 v[234:235], v191 offset:0x3200
	ds_read_b64_tr_b16 v[236:237], v191 offset:0x3a00
	s_waitcnt lgkmcnt(0)
	v_mfma_f32_32x32x16_bf16 v[48:63], v[80:83], v[214:217], v[48:63]
	ds_read_b64_tr_b16 v[214:215], v191 offset:0x400
	ds_read_b64_tr_b16 v[216:217], v191 offset:0xc00
	v_mfma_f32_32x32x16_bf16 v[48:63], v[84:87], v[218:221], v[48:63]
	ds_read_b64_tr_b16 v[218:219], v191 offset:0x1400
	ds_read_b64_tr_b16 v[220:221], v191 offset:0x1c00
	v_mfma_f32_32x32x16_bf16 v[48:63], v[88:91], v[222:225], v[48:63]
	ds_read_b64_tr_b16 v[222:223], v191 offset:0x2400
	ds_read_b64_tr_b16 v[224:225], v191 offset:0x2c00
	v_mfma_f32_32x32x16_bf16 v[48:63], v[92:95], v[234:237], v[48:63]
	ds_read_b64_tr_b16 v[234:235], v191 offset:0x3400
	ds_read_b64_tr_b16 v[236:237], v191 offset:0x3c00
	s_waitcnt lgkmcnt(0)
	v_mfma_f32_32x32x16_bf16 v[32:47], v[80:83], v[214:217], v[32:47]
	ds_read_b64_tr_b16 v[214:215], v191 offset:0x600
	ds_read_b64_tr_b16 v[216:217], v191 offset:0xe00
	v_mfma_f32_32x32x16_bf16 v[32:47], v[84:87], v[218:221], v[32:47]
	ds_read_b64_tr_b16 v[218:219], v191 offset:0x1600
	ds_read_b64_tr_b16 v[220:221], v191 offset:0x1e00
	v_mfma_f32_32x32x16_bf16 v[32:47], v[88:91], v[222:225], v[32:47]
	ds_read_b64_tr_b16 v[222:223], v191 offset:0x2600
	ds_read_b64_tr_b16 v[224:225], v191 offset:0x2e00
	v_mfma_f32_32x32x16_bf16 v[32:47], v[92:95], v[234:237], v[32:47]
	ds_read_b64_tr_b16 v[234:235], v191 offset:0x3600
	ds_read_b64_tr_b16 v[236:237], v191 offset:0x3e00
	s_waitcnt lgkmcnt(0)
	v_mfma_f32_32x32x16_bf16 v[16:31], v[80:83], v[214:217], v[16:31]
	s_waitcnt vmcnt(4)
	ds_write_b128 v195, v[170:173] offset:49152
	ds_write_b128 v196, v[174:177] offset:49152
	v_mfma_f32_32x32x16_bf16 v[16:31], v[84:87], v[218:221], v[16:31]
	v_mfma_f32_32x32x16_bf16 v[16:31], v[88:91], v[222:225], v[16:31]
	v_mfma_f32_32x32x16_bf16 v[16:31], v[92:95], v[234:237], v[16:31]
	v_cmp_ge_f32_e32 vcc, s45, v180
	s_cmp_eq_u64 vcc, exec
	v_mov_b32_e32 v170, 1.0
	s_cbranch_scc0 .LBB0_166

; #define SBAR() __builtin_amdgcn_sched_barrier(0)
; #define KWRITE(b, src0, src1) do { if constexpr (ND0 == 4) { *(bf16x8*)(K_lds + (b) * SHM_K + KSWZ(kr, kcb)) = src0; } \
;     else { int kc = sc * 2; *(bf16x8*)(K_lds + (b) * SHM_K + KSWZ(sr, kc)) = src0; *(bf16x8*)(K_lds + (b) * SHM_K + KSWZ(32 + sr, kc)) = src1; } } while (0)
; #define SLOAD_A(k0) do { vs0a = *reinterpret_cast<const bf16x8*>(&Vh[(long)((k0) + sr) * LDK + sc]); vs1a = *reinterpret_cast<const bf16x8*>(&Vh[(long)((k0) + 32 + sr) * LDK + sc]); KLOAD(ks0a, ks1a, k0); } while (0)
; #define SLOAD_B(k0) do { vs0b = *reinterpret_cast<const bf16x8*>(&Vh[(long)((k0) + sr) * LDK + sc]); vs1b = *reinterpret_cast<const bf16x8*>(&Vh[(long)((k0) + 32 + sr) * LDK + sc]); KLOAD(ks0b, ks1b, k0); } while (0)
; #define VWRITE_A(b) do { *(bf16x8*)(V_lds + (b) * SHM_V + vst0) = vs0a; *(bf16x8*)(V_lds + (b) * SHM_V + vst1) = vs1a; } while (0)
; #define VWRITE_B(b) do { *(bf16x8*)(V_lds + (b) * SHM_V + vst0) = vs0b; *(bf16x8*)(V_lds + (b) * SHM_V + vst1) = vs1b; } while (0)
; #define SWAIT() do { if constexpr (ND0 == 4) asm volatile("s_waitcnt vmcnt(3)" ::: "memory"); else asm volatile("s_waitcnt vmcnt(4)" ::: "memory"); } while (0)
; #define PSM(P0, P1, MN, AL) do { if constexpr (PRE) partialSM_pre(P0, P1, m_reg, AL, 11.541560327111707f); else partialSM(P0, P1, m_reg, MN, AL, C, thr_raw); } while (0)
; __device__ __forceinline__ void finishSM(f32x16& p0, f32x16& p1, float alpha, float& l_reg, bf16x8& pa0, bf16x8& pa1, bf16x8& pa2, bf16x8& pa3) {
;     ...
;   l_reg = l_reg * alpha + ps;
; template <int ND0, int LDQ, int LDK, int LDO> ...
;     ...
;   for (int j = 1; j + 1 < NT; j += 2) {
;     SBAR(); qkt<ND0>(pB0, pB1, Kq1, qr, r32, hi);
;     finishSM(pA0, pA1, alA, l_reg, pa0, pa1, pa2, pa3); SBAR();
;     SLOAD_B((j + 2) * KVBLK); SBAR();
;     pv_d0(o, vb0, pa0, pa1, pa2, pa3); KWRITE(0, ks0a, ks1a); PSM(pB0, pB1, mnB, alB);
;     __syncthreads(); SWAIT(); VWRITE_A(0);
;     RESC(alB); __syncthreads();
;     SBAR(); qkt<ND0>(pA0, pA1, Kq0, qr, r32, hi);
;     finishSM(pB0, pB1, alB, l_reg, pa0, pa1, pa2, pa3); SBAR();
;     if (j + 3 < NT) SLOAD_A((j + 3) * KVBLK); SBAR();
;     pv_d0(o, vb0 + (int)SHM_V, pa0, pa1, pa2, pa3); KWRITE(1, ks0b, ks1b); PSM(pA0, pA1, mnA, alA);
;     __syncthreads(); SWAIT(); VWRITE_B(1);
;     RESC(alA); __syncthreads();
;   }
.LBB0_161:
	v_add_f32_e32 v80, v208, v209
	v_fmac_f32_e32 v80, v207, v192
	v_add_f32_e32 v192, v211, v212
	v_fmac_f32_e32 v192, v80, v210
	ds_read_b128 v[80:83], v199 offset:49152
	ds_read_b128 v[84:87], v199 offset:57344
	v_exp_f32_e32 v176, v96
	v_exp_f32_e32 v213, v97
	v_exp_f32_e32 v174, v98
	v_exp_f32_e32 v177, v99
	v_exp_f32_e32 v173, v100
	v_exp_f32_e32 v175, v101
	v_exp_f32_e32 v171, v102
	v_exp_f32_e32 v172, v103
	v_exp_f32_e32 v167, v104
	v_exp_f32_e32 v169, v105
	v_exp_f32_e32 v166, v106
	v_exp_f32_e32 v168, v107
	v_exp_f32_e32 v163, v108
	v_exp_f32_e32 v165, v109
	v_exp_f32_e32 v162, v110
	v_exp_f32_e32 v164, v111
	v_lshl_add_u64 v[188:189], v[188:189], 0, s[42:43]
	s_and_b64 vcc, exec, s[4:5]
	s_cbranch_vccnz .LBB0_167
	v_mov_b32_e32 v207, v170
	s_branch .LBB0_146

; __device__ __forceinline__ void partialSM_pre(f32x16& p0, f32x16& p1, float& m_ref, float& alpha, const float thr2) {
;     ...
;   if (__builtin_expect(__all(pmax <= thr2), 1)) { alpha = 1.f; }
;   else { const float dl = fmaxf(pmax, 0.f); m_ref += dl; alpha = __builtin_amdgcn_exp2f(-dl);
; #pragma unroll
;     for (int r = 0; r < 16; ++r) { p0[r] -= dl; p1[r] -= dl; } }
.LBB0_164:
	v_max_f32_e32 v180, v180, v180
	v_max_f32_e32 v180, 0, v180
	v_exp_f32_e64 v210, -v180
	v_add_f32_e32 v193, v193, v180
	v_pk_add_f32 v[96:97], v[96:97], v[180:181] op_sel_hi:[1,0] neg_lo:[0,1] neg_hi:[0,1]
	v_pk_add_f32 v[98:99], v[98:99], v[180:181] op_sel_hi:[1,0] neg_lo:[0,1] neg_hi:[0,1]
	v_pk_add_f32 v[100:101], v[100:101], v[180:181] op_sel_hi:[1,0] neg_lo:[0,1] neg_hi:[0,1]
	v_pk_add_f32 v[102:103], v[102:103], v[180:181] op_sel_hi:[1,0] neg_lo:[0,1] neg_hi:[0,1]
	v_pk_add_f32 v[104:105], v[104:105], v[180:181] op_sel_hi:[1,0] neg_lo:[0,1] neg_hi:[0,1]
	v_pk_add_f32 v[106:107], v[106:107], v[180:181] op_sel_hi:[1,0] neg_lo:[0,1] neg_hi:[0,1]
	v_pk_add_f32 v[108:109], v[108:109], v[180:181] op_sel_hi:[1,0] neg_lo:[0,1] neg_hi:[0,1]
	v_pk_add_f32 v[110:111], v[110:111], v[180:181] op_sel_hi:[1,0] neg_lo:[0,1] neg_hi:[0,1]
	v_sub_f32_e32 v95, v95, v180
	v_sub_f32_e32 v94, v94, v180
	v_sub_f32_e32 v93, v93, v180
	v_sub_f32_e32 v92, v92, v180
	v_sub_f32_e32 v91, v91, v180
	v_sub_f32_e32 v90, v90, v180
	v_sub_f32_e32 v89, v89, v180
	v_sub_f32_e32 v88, v88, v180
	v_sub_f32_e32 v87, v87, v180
	v_sub_f32_e32 v86, v86, v180
	v_sub_f32_e32 v85, v85, v180
	v_sub_f32_e32 v84, v84, v180
	v_sub_f32_e32 v83, v83, v180
	v_sub_f32_e32 v82, v82, v180
	v_sub_f32_e32 v81, v81, v180
	v_sub_f32_e32 v80, v80, v180
	s_branch .LBB0_148

; #define SBAR() __builtin_amdgcn_sched_barrier(0)
; __device__ __forceinline__ void partialSM_pre(f32x16& p0, f32x16& p1, float& m_ref, float& alpha, const float thr2) {
;     ...
;   if (__builtin_expect(__all(pmax <= thr2), 1)) { alpha = 1.f; }
;   else { const float dl = fmaxf(pmax, 0.f); m_ref += dl; alpha = __builtin_amdgcn_exp2f(-dl);
; #pragma unroll
;     for (int r = 0; r < 16; ++r) { p0[r] -= dl; p1[r] -= dl; } }
; template <int ND0, int LDQ, int LDK, int LDO> ...
;     ...
;   SBAR(); qkt<ND0>(pB0, pB1, Kq1, qr, r32, hi);
;   finishSM(pA0, pA1, alA, l_reg, pa0, pa1, pa2, pa3); SBAR();
.LBB0_166:
	v_max_f32_e32 v180, v180, v180
	v_max_f32_e32 v180, 0, v180
	v_exp_f32_e64 v170, -v180
	v_add_f32_e32 v193, v193, v180
	v_pk_add_f32 v[96:97], v[96:97], v[180:181] op_sel_hi:[1,0] neg_lo:[0,1] neg_hi:[0,1]
	v_pk_add_f32 v[98:99], v[98:99], v[180:181] op_sel_hi:[1,0] neg_lo:[0,1] neg_hi:[0,1]
	v_pk_add_f32 v[100:101], v[100:101], v[180:181] op_sel_hi:[1,0] neg_lo:[0,1] neg_hi:[0,1]
	v_pk_add_f32 v[102:103], v[102:103], v[180:181] op_sel_hi:[1,0] neg_lo:[0,1] neg_hi:[0,1]
	v_pk_add_f32 v[104:105], v[104:105], v[180:181] op_sel_hi:[1,0] neg_lo:[0,1] neg_hi:[0,1]
	v_pk_add_f32 v[106:107], v[106:107], v[180:181] op_sel_hi:[1,0] neg_lo:[0,1] neg_hi:[0,1]
	v_pk_add_f32 v[108:109], v[108:109], v[180:181] op_sel_hi:[1,0] neg_lo:[0,1] neg_hi:[0,1]
	v_pk_add_f32 v[110:111], v[110:111], v[180:181] op_sel_hi:[1,0] neg_lo:[0,1] neg_hi:[0,1]
	v_sub_f32_e32 v79, v79, v180
	v_sub_f32_e32 v78, v78, v180
	v_sub_f32_e32 v77, v77, v180
	v_sub_f32_e32 v76, v76, v180
	v_sub_f32_e32 v75, v75, v180
	v_sub_f32_e32 v74, v74, v180
	v_sub_f32_e32 v73, v73, v180
	v_sub_f32_e32 v72, v72, v180
	v_sub_f32_e32 v71, v71, v180
	v_sub_f32_e32 v70, v70, v180
	v_sub_f32_e32 v69, v69, v180
	v_sub_f32_e32 v68, v68, v180
	v_sub_f32_e32 v67, v67, v180
	v_sub_f32_e32 v66, v66, v180
	v_sub_f32_e32 v65, v65, v180
	v_sub_f32_e32 v64, v64, v180
	s_branch .LBB0_157
.LBB0_167:
	v_exp_f32_e32 v78, v78
	v_exp_f32_e32 v79, v79
	s_waitcnt lgkmcnt(1)
	v_mfma_f32_32x32x16_bf16 v[96:111], v[80:83], v[114:117], 0
	s_waitcnt lgkmcnt(0)
	v_mfma_f32_32x32x16_bf16 v[80:95], v[84:87], v[114:117], 0
	ds_read_b128 v[114:117], v200 offset:49152
	ds_read_b128 v[146:149], v200 offset:57344
	s_waitcnt lgkmcnt(1)
	v_mfma_f32_32x32x16_bf16 v[96:111], v[114:117], v[122:125], v[96:111]
	s_waitcnt lgkmcnt(0)
	v_mfma_f32_32x32x16_bf16 v[80:95], v[146:149], v[122:125], v[80:95]
	ds_read_b128 v[114:117], v202 offset:49152
	ds_read_b128 v[122:125], v202 offset:57344
	s_waitcnt lgkmcnt(1)
	v_mfma_f32_32x32x16_bf16 v[96:111], v[114:117], v[142:145], v[96:111]
	s_waitcnt lgkmcnt(0)
	v_mfma_f32_32x32x16_bf16 v[80:95], v[122:125], v[142:145], v[80:95]
	ds_read_b128 v[114:117], v201 offset:49152
	ds_read_b128 v[122:125], v201 offset:57344
	s_waitcnt lgkmcnt(1)
	v_mfma_f32_32x32x16_bf16 v[96:111], v[114:117], v[138:141], v[96:111]
	s_waitcnt lgkmcnt(0)
	v_mfma_f32_32x32x16_bf16 v[80:95], v[122:125], v[138:141], v[80:95]
	ds_read_b128 v[114:117], v203 offset:49152
	ds_read_b128 v[122:125], v203 offset:57344
	s_waitcnt lgkmcnt(1)
	v_mfma_f32_32x32x16_bf16 v[96:111], v[114:117], v[134:137], v[96:111]
	s_waitcnt lgkmcnt(0)
	v_mfma_f32_32x32x16_bf16 v[80:95], v[122:125], v[134:137], v[80:95]
	ds_read_b128 v[114:117], v204 offset:49152
	ds_read_b128 v[122:125], v204 offset:57344
	s_waitcnt lgkmcnt(1)
	v_mfma_f32_32x32x16_bf16 v[96:111], v[114:117], v[130:133], v[96:111]
	s_waitcnt lgkmcnt(0)
	v_mfma_f32_32x32x16_bf16 v[80:95], v[122:125], v[130:133], v[80:95]
	ds_read_b128 v[114:117], v206 offset:49152
	ds_read_b128 v[122:125], v206 offset:57344
	s_waitcnt lgkmcnt(1)
	v_mfma_f32_32x32x16_bf16 v[96:111], v[114:117], v[126:129], v[96:111]
	s_waitcnt lgkmcnt(0)
	v_mfma_f32_32x32x16_bf16 v[80:95], v[122:125], v[126:129], v[80:95]
	ds_read_b128 v[114:117], v205 offset:49152
	ds_read_b128 v[122:125], v205 offset:57344
	v_exp_f32_e32 v126, v76
	v_exp_f32_e32 v127, v77
	s_waitcnt lgkmcnt(1)
	v_mfma_f32_32x32x16_bf16 v[96:111], v[114:117], v[118:121], v[96:111]
	v_exp_f32_e32 v114, v64
	v_add_f32_e32 v64, 0, v176
	v_add_f32_e32 v64, v213, v64
	v_add_f32_e32 v64, v174, v64
	v_add_f32_e32 v64, v177, v64
	v_add_f32_e32 v64, v173, v64
	v_add_f32_e32 v64, v175, v64
	v_add_f32_e32 v64, v171, v64
	v_add_f32_e32 v64, v172, v64
	v_add_f32_e32 v64, v167, v64
	v_add_f32_e32 v64, v169, v64
	v_add_f32_e32 v64, v166, v64
	v_add_f32_e32 v64, v168, v64
	v_add_f32_e32 v64, v163, v64
	v_exp_f32_e32 v115, v65
	v_add_f32_e32 v64, v165, v64
	v_exp_f32_e32 v116, v66
	v_add_f32_e32 v64, v162, v64
	v_exp_f32_e32 v117, v67
	v_add_f32_e32 v64, v164, v64
	s_waitcnt lgkmcnt(0)
; #define SBAR() __builtin_amdgcn_sched_barrier(0)
; #define PSM(P0, P1, MN, AL) do { if constexpr (PRE) partialSM_pre(P0, P1, m_reg, AL, 11.541560327111707f); else partialSM(P0, P1, m_reg, MN, AL, C, thr_raw); } while (0)
; #define RESC(a) do { if (__any((a) < 1.f)) { if (hi == 0) al_l[r32] = (a); asm volatile("s_waitcnt lgkmcnt(0)" ::: "memory"); \
;     _Pragma("unroll") for (int d = 0; d < 4; ++d) _Pragma("unroll") for (int r = 0; r < 16; ++r) o[d][r] *= al_l[crow(r, hi)]; } } while (0)
; __device__ __forceinline__ void finishSM(f32x16& p0, f32x16& p1, float alpha, float& l_reg, bf16x8& pa0, bf16x8& pa1, bf16x8& pa2, bf16x8& pa3) {
; #pragma unroll
;   for (int r = 0; r < 16; ++r) p1[r] = __builtin_amdgcn_exp2f(p1[r]);
;   float ps = 0;
; #pragma unroll
;   for (int r = 0; r < 16; ++r) ps += p0[r];
; #pragma unroll
;   for (int r = 0; r < 16; ++r) ps += p1[r];
;   { auto rr = __builtin_amdgcn_permlane32_swap(__float_as_uint(ps), __float_as_uint(ps), false, false);
;     ps = __uint_as_float(rr[0]) + __uint_as_float(rr[1]); }
;   l_reg = l_reg * alpha + ps;
;     ...
;   PK4(p0, 0, pa0); PK4(p0, 8, pa1); PK4(p1, 0, pa2); PK4(p1, 8, pa3);
; template <int ND0, int LDQ, int LDK, int LDO> ...
;     ...
;   finishSM(pA0, pA1, alA, l_reg, pa0, pa1, pa2, pa3); SBAR();
;   pv_d0(o, vb0, pa0, pa1, pa2, pa3); PSM(pB0, pB1, mnB, alB);
;   __syncthreads(); RESC(alB);
	v_mfma_f32_32x32x16_bf16 v[80:95], v[122:125], v[118:121], v[80:95]
	v_exp_f32_e32 v118, v68
	v_add_f32_e32 v64, v114, v64
	v_exp_f32_e32 v119, v69
	v_add_f32_e32 v64, v115, v64
	v_exp_f32_e32 v120, v70
	v_add_f32_e32 v64, v116, v64
	v_exp_f32_e32 v121, v71
	v_add_f32_e32 v64, v117, v64
	v_exp_f32_e32 v122, v72
	v_add_f32_e32 v64, v118, v64
	v_exp_f32_e32 v123, v73
	v_add_f32_e32 v64, v119, v64
	v_exp_f32_e32 v124, v74
	v_add_f32_e32 v64, v120, v64
	v_exp_f32_e32 v125, v75
	v_add_f32_e32 v64, v121, v64
	v_add_f32_e32 v64, v122, v64
	v_add_f32_e32 v64, v123, v64
	v_add_f32_e32 v64, v124, v64
	v_add_f32_e32 v64, v125, v64
	v_add_f32_e32 v64, v126, v64
	v_add_f32_e32 v64, v127, v64
	v_add_f32_e32 v64, v78, v64
	v_add_f32_e32 v68, v79, v64
	v_mov_b32_e32 v69, v68
	s_nop 1
	v_permlane32_swap_b32_e32 v68, v69
	v_cvt_pk_bf16_f32 v64, v176, v213
	v_cvt_pk_bf16_f32 v65, v174, v177
	v_cvt_pk_bf16_f32 v66, v173, v175
	v_cvt_pk_bf16_f32 v67, v171, v172
	v_cvt_pk_bf16_f32 v70, v167, v169
	v_cvt_pk_bf16_f32 v71, v166, v168
	v_cvt_pk_bf16_f32 v72, v163, v165
	v_cvt_pk_bf16_f32 v73, v162, v164
	v_cvt_pk_bf16_f32 v74, v114, v115
	v_cvt_pk_bf16_f32 v75, v116, v117
	v_cvt_pk_bf16_f32 v76, v118, v119
	v_cvt_pk_bf16_f32 v77, v120, v121
	v_cvt_pk_bf16_f32 v114, v122, v123
	v_cvt_pk_bf16_f32 v115, v124, v125
	v_cvt_pk_bf16_f32 v116, v126, v127
	v_cvt_pk_bf16_f32 v117, v78, v79
	s_nop 0
	v_permlane32_swap_b32_e32 v64, v66
	v_permlane32_swap_b32_e32 v65, v67
	v_permlane32_swap_b32_e32 v70, v72
	v_permlane32_swap_b32_e32 v71, v73
	v_permlane32_swap_b32_e32 v74, v76
	v_permlane32_swap_b32_e32 v75, v77
	v_permlane32_swap_b32_e32 v114, v116
	v_permlane32_swap_b32_e32 v115, v117
	ds_read_b64_tr_b16 v[118:119], v194 offset:0
	ds_read_b64_tr_b16 v[120:121], v194 offset:0x800
	ds_read_b64_tr_b16 v[122:123], v194 offset:0x1000
	ds_read_b64_tr_b16 v[124:125], v194 offset:0x1800
	ds_read_b64_tr_b16 v[126:127], v194 offset:0x2000
	ds_read_b64_tr_b16 v[128:129], v194 offset:0x2800
	ds_read_b64_tr_b16 v[130:131], v194 offset:0x3000
	ds_read_b64_tr_b16 v[132:133], v194 offset:0x3800
	s_waitcnt lgkmcnt(0)
	s_nop 0
	v_mfma_f32_32x32x16_bf16 v[0:15], v[64:67], v[118:121], v[0:15]
	ds_read_b64_tr_b16 v[118:119], v194 offset:0x200
	ds_read_b64_tr_b16 v[120:121], v194 offset:0xa00
	v_mfma_f32_32x32x16_bf16 v[0:15], v[70:73], v[122:125], v[0:15]
	ds_read_b64_tr_b16 v[122:123], v194 offset:0x1200
	ds_read_b64_tr_b16 v[124:125], v194 offset:0x1a00
	v_mfma_f32_32x32x16_bf16 v[0:15], v[74:77], v[126:129], v[0:15]
	ds_read_b64_tr_b16 v[126:127], v194 offset:0x2200
	ds_read_b64_tr_b16 v[128:129], v194 offset:0x2a00
	v_mfma_f32_32x32x16_bf16 v[0:15], v[114:117], v[130:133], v[0:15]
	ds_read_b64_tr_b16 v[130:131], v194 offset:0x3200
	ds_read_b64_tr_b16 v[132:133], v194 offset:0x3a00
	s_waitcnt lgkmcnt(0)
	v_mfma_f32_32x32x16_bf16 v[48:63], v[64:67], v[118:121], v[48:63]
	ds_read_b64_tr_b16 v[118:119], v194 offset:0x400
	ds_read_b64_tr_b16 v[120:121], v194 offset:0xc00
	v_mfma_f32_32x32x16_bf16 v[48:63], v[70:73], v[122:125], v[48:63]
	ds_read_b64_tr_b16 v[122:123], v194 offset:0x1400
	ds_read_b64_tr_b16 v[124:125], v194 offset:0x1c00
	v_mfma_f32_32x32x16_bf16 v[48:63], v[74:77], v[126:129], v[48:63]
	ds_read_b64_tr_b16 v[126:127], v194 offset:0x2400
	ds_read_b64_tr_b16 v[128:129], v194 offset:0x2c00
	v_mfma_f32_32x32x16_bf16 v[48:63], v[114:117], v[130:133], v[48:63]
	ds_read_b64_tr_b16 v[130:131], v194 offset:0x3400
	ds_read_b64_tr_b16 v[132:133], v194 offset:0x3c00
	s_waitcnt lgkmcnt(0)
	v_mfma_f32_32x32x16_bf16 v[32:47], v[64:67], v[118:121], v[32:47]
	ds_read_b64_tr_b16 v[118:119], v194 offset:0x600
	ds_read_b64_tr_b16 v[120:121], v194 offset:0xe00
	v_mfma_f32_32x32x16_bf16 v[32:47], v[70:73], v[122:125], v[32:47]
	ds_read_b64_tr_b16 v[122:123], v194 offset:0x1600
	ds_read_b64_tr_b16 v[124:125], v194 offset:0x1e00
	v_mfma_f32_32x32x16_bf16 v[32:47], v[74:77], v[126:129], v[32:47]
	ds_read_b64_tr_b16 v[126:127], v194 offset:0x2600
	ds_read_b64_tr_b16 v[128:129], v194 offset:0x2e00
	v_mfma_f32_32x32x16_bf16 v[32:47], v[114:117], v[130:133], v[32:47]
	ds_read_b64_tr_b16 v[130:131], v194 offset:0x3600
	ds_read_b64_tr_b16 v[132:133], v194 offset:0x3e00
	s_waitcnt lgkmcnt(0)
	v_mfma_f32_32x32x16_bf16 v[16:31], v[64:67], v[118:121], v[16:31]
	v_cmp_neq_f32_e32 vcc, 0, v193
	v_mfma_f32_32x32x16_bf16 v[16:31], v[70:73], v[122:125], v[16:31]
	v_mfma_f32_32x32x16_bf16 v[16:31], v[74:77], v[126:129], v[16:31]
	v_mfma_f32_32x32x16_bf16 v[16:31], v[114:117], v[130:133], v[16:31]
	s_cbranch_vccnz .LBB0_176

; #define SBAR() __builtin_amdgcn_sched_barrier(0)
; __device__ __forceinline__ int v_st(int k, int c) { const int kk = (k & ~0xC) | ((k & 4) << 1) | ((k & 8) >> 1); return ((kk >> 3) * 4 + (c >> 5)) * 512 + ((kk & 7) * 32 + (c & 31)) * 2; }
; __device__ __forceinline__ int v_rd_base(int lane) { return ((lane & 3) << 3) | (((lane >> 2) & 3) << 6) | (((lane >> 4) & 1) << 5) | (((lane >> 5) & 1) << 8); }
; #define SLOAD_A(k0) do { vs0a = *reinterpret_cast<const bf16x8*>(&Vh[(long)((k0) + sr) * LDK + sc]); vs1a = *reinterpret_cast<const bf16x8*>(&Vh[(long)((k0) + 32 + sr) * LDK + sc]); KLOAD(ks0a, ks1a, k0); } while (0)
; #define SLOAD_B(k0) do { vs0b = *reinterpret_cast<const bf16x8*>(&Vh[(long)((k0) + sr) * LDK + sc]); vs1b = *reinterpret_cast<const bf16x8*>(&Vh[(long)((k0) + 32 + sr) * LDK + sc]); KLOAD(ks0b, ks1b, k0); } while (0)
; #define SWRITE_A(b) do { *(bf16x8*)(V_lds + (b) * SHM_V + vst0) = vs0a; *(bf16x8*)(V_lds + (b) * SHM_V + vst1) = vs1a; KWRITE(b, ks0a, ks1a); } while (0)
; #define SWRITE_B(b) do { *(bf16x8*)(V_lds + (b) * SHM_V + vst0) = vs0b; *(bf16x8*)(V_lds + (b) * SHM_V + vst1) = vs1b; KWRITE(b, ks0b, ks1b); } while (0)
; template <int ND0, int LDQ, int LDK, int LDO> ...
;     ...
;   float m_reg = PRE ? 0.f : -1e30f, l_reg = 0; f32x16 o[4] = {}; bf16x8 qr[ND0];
;   const bf16_t* Qw = Qb + (long)(wid * QBLK + r32) * LDQ + hi * 8;
; #pragma unroll
;   for (int d0 = 0; d0 < ND0; ++d0) qr[d0] = *reinterpret_cast<const bf16x8*>(Qw + d0 * 16);
;   const int sr = tid >> 4, sc = (tid & 15) * 8, vst0 = v_st(sr, sc), vst1 = v_st(32 + sr, sc);
;   const int vb0 = (int)(uintptr_t)V_lds + v_rd_base(lane);
;   bf16x8 vs0a, vs1a, ks0a, ks1a = {}, vs0b, vs1b, ks0b, ks1b = {};
;   const int kr = tid >> 3, kcb = kofs + (tid & 7) * 16;
;     ...
;   f32x16 pA0, pA1, pB0, pB1; float mnA, mnB, alA, alB; bf16x8 pa0, pa1, pa2, pa3; const int NT = seq / KVBLK;
;   const char* Kq0 = K_lds + kofs; const char* Kq1 = K_lds + SHM_K + kofs;
;   if (ND0 == 4 && have_pf) { vs0a = pfv0; vs1a = pfv1; ks0a = pfk0; } else { SLOAD_A(0); }
;   asm volatile("s_waitcnt vmcnt(0)" ::: "memory"); SWRITE_A(0); __syncthreads();
;   qkt<ND0>(pA0, pA1, Kq0, qr, r32, hi); PSM(pA0, pA1, mnA, alA);
;   SLOAD_B(KVBLK); if (2 < NT) SLOAD_A(2 * KVBLK);
;   SWAIT(); SWRITE_B(1); __syncthreads();
;   for (int j = 1; j + 1 < NT; j += 2) {
;     SBAR(); qkt<ND0>(pB0, pB1, Kq1, qr, r32, hi);
.LBB0_213:
	v_add_u32_e32 v17, 64, v21
	v_mov_b64_e32 v[36:37], s[20:21]
	v_mad_i64_i32 v[24:25], s[20:21], v17, s44, v[36:37]
	v_add_u32_e32 v17, 0x60, v21
	v_mov_b32_e32 v161, v113
	v_mad_i64_i32 v[26:27], s[20:21], v17, s44, v[36:37]
	v_add_u32_e32 v17, 64, v22
	v_mov_b64_e32 v[38:39], s[18:19]
	v_add_u32_e32 v23, 0x80, v22
	v_lshl_add_u64 v[24:25], v[24:25], 0, v[160:161]
	v_lshl_add_u64 v[28:29], v[26:27], 0, v[160:161]
	v_mov_b32_e32 v19, v113
	v_mad_i64_i32 v[32:33], s[18:19], v17, s44, v[38:39]
	v_add_u32_e32 v40, 0xa0, v21
	v_add_u32_e32 v42, 0x80, v21
	v_mad_i64_i32 v[38:39], s[18:19], v23, s44, v[38:39]
	global_load_dwordx4 v[24:27], v[24:25], off
	s_nop 0
	global_load_dwordx4 v[28:31], v[28:29], off
	v_lshl_add_u64 v[32:33], v[32:33], 0, v[18:19]
	v_mad_i64_i32 v[40:41], s[18:19], v40, s44, v[36:37]
	v_mad_i64_i32 v[36:37], s[18:19], v42, s44, v[36:37]
	v_lshl_add_u64 v[38:39], v[38:39], 0, v[18:19]
	global_load_dwordx4 v[32:35], v[32:33], off offset:2048
	v_lshl_add_u64 v[40:41], v[40:41], 0, v[160:161]
	v_lshl_add_u64 v[36:37], v[36:37], 0, v[160:161]
	global_load_dwordx4 v[138:141], v[38:39], off offset:2048
	global_load_dwordx4 v[134:137], v[40:41], off
	global_load_dwordx4 v[130:133], v[36:37], off
	v_and_b32_e32 v185, 63, v20
	s_lshl_b32 s38, s38, 7
	s_add_i32 s20, 0, 0x10000
	v_exp_f32_e32 v177, v3
	v_lshlrev_b32_e32 v3, 4, v185
	v_exp_f32_e32 v174, v2
	v_exp_f32_e32 v152, v4
	v_mad_i64_i32 v[166:167], s[18:19], v22, s44, 0
	v_lshlrev_b32_e32 v2, 3, v185
	v_lshlrev_b32_e32 v4, 1, v185
	s_cmp_lg_u32 0, -1
	v_and_b32_e32 v3, 0xc0, v3
	v_exp_f32_e32 v175, v5
	v_and_b32_e32 v4, 32, v4
	v_and_b32_e32 v5, 0x100, v2
	s_cselect_b32 s18, 0, 0
	v_and_or_b32 v2, v2, 24, v3
	v_cndmask_b32_e64 v19, 0, 1, s[2:3]
	v_exp_f32_e32 v176, v0
	v_exp_f32_e32 v206, v1
	v_mov_b64_e32 v[0:1], s[6:7]
	s_add_i32 s19, s18, 0x4000
	v_or3_b32 v2, v2, v4, v5
	v_readlane_b32 s48, v254, 14
	v_add_u32_e32 v192, s18, v2
	v_add_u32_e32 v190, s19, v2
	v_mad_i64_i32 v[2:3], s[18:19], v22, s44, v[0:1]
	v_lshl_or_b32 v4, v19, 7, v16
	v_mov_b32_e32 v5, v113
	v_readlane_b32 s50, v254, 16
	v_readlane_b32 s51, v254, 17
	v_lshl_add_u64 v[2:3], v[2:3], 0, v[4:5]
	s_mov_b64 s[42:43], s[50:51]
	v_lshl_add_u64 v[170:171], s[42:43], 0, v[2:3]
	v_and_b32_e32 v2, 15, v20
	v_exp_f32_e32 v151, v6
	v_exp_f32_e32 v153, v7
	v_exp_f32_e32 v147, v8
	v_exp_f32_e32 v149, v9
	v_exp_f32_e32 v145, v10
	v_exp_f32_e32 v148, v11
	v_exp_f32_e32 v143, v12
	v_exp_f32_e32 v146, v13
	v_exp_f32_e32 v142, v14
	v_exp_f32_e32 v144, v15
	v_mad_i64_i32 v[0:1], s[18:19], v21, s44, v[0:1]
	v_lshlrev_b32_e32 v2, 4, v2
	v_mov_b32_e32 v3, v113
	v_and_b32_e32 v17, 0x3fffffc0, v20
	s_waitcnt vmcnt(3)
	v_lshl_add_u64 v[0:1], v[0:1], 0, v[2:3]
	v_mov_b32_e32 v14, v113
	v_mov_b32_e32 v15, v113
	v_lshrrev_b32_e32 v188, 1, v18
	v_lshl_add_u32 v161, v17, 2, s20
	s_waitcnt vmcnt(5)
	ds_write_b128 v193, v[24:27] offset:16384
	s_waitcnt vmcnt(4)
	ds_write_b128 v194, v[28:31] offset:16384
	s_waitcnt vmcnt(3)
	ds_write_b128 v195, v[32:35] offset:49152
	v_mad_i64_i32 v[168:169], s[18:19], v21, s44, 0
	v_lshl_add_u64 v[172:173], s[42:43], 0, v[0:1]
	v_mov_b32_e32 v0, v113
	v_mov_b32_e32 v1, v113
	v_mov_b32_e32 v2, v113
	v_mov_b32_e32 v4, v113
	v_mov_b32_e32 v6, v113
	v_mov_b32_e32 v7, v113
	v_mov_b32_e32 v8, v113
	v_mov_b32_e32 v9, v113
	v_mov_b32_e32 v10, v113
	v_mov_b32_e32 v11, v113
	v_mov_b32_e32 v12, v113
	v_mov_b32_e32 v13, v113
	v_mov_b64_e32 v[62:63], v[14:15]
	v_mov_b64_e32 v[46:47], v[14:15]
	v_mov_b64_e32 v[30:31], v[14:15]
	s_mov_b32 s40, 4
	v_cmp_gt_u32_e64 s[6:7], 32, v185
	v_lshl_add_u32 v187, v157, 2, v161
	v_mov_b32_e32 v189, 0
	v_mov_b64_e32 v[60:61], v[12:13]
	v_mov_b64_e32 v[58:59], v[10:11]
	v_mov_b64_e32 v[56:57], v[8:9]
	v_mov_b64_e32 v[54:55], v[6:7]
	v_mov_b64_e32 v[52:53], v[4:5]
	v_mov_b64_e32 v[50:51], v[2:3]
	v_mov_b64_e32 v[48:49], v[0:1]
	v_mov_b64_e32 v[44:45], v[12:13]
	v_mov_b64_e32 v[42:43], v[10:11]
	v_mov_b64_e32 v[40:41], v[8:9]
	v_mov_b64_e32 v[38:39], v[6:7]
	v_mov_b64_e32 v[36:37], v[4:5]
	v_mov_b64_e32 v[34:35], v[2:3]
	v_mov_b64_e32 v[32:33], v[0:1]
	v_mov_b64_e32 v[28:29], v[12:13]
	v_mov_b64_e32 v[26:27], v[10:11]
	v_mov_b64_e32 v[24:25], v[8:9]
	v_mov_b64_e32 v[22:23], v[6:7]
	v_mov_b64_e32 v[20:21], v[4:5]
	v_mov_b64_e32 v[18:19], v[2:3]
	v_mov_b64_e32 v[16:17], v[0:1]
	s_waitcnt lgkmcnt(0)
	s_barrier
	v_readlane_b32 s49, v254, 15
	ds_read_b128 v[80:83], v197 offset:49152
	ds_read_b128 v[84:87], v197 offset:57344
; #define SBAR() __builtin_amdgcn_sched_barrier(0)
; #define SLOAD_B(k0) do { vs0b = *reinterpret_cast<const bf16x8*>(&Vh[(long)((k0) + sr) * LDK + sc]); vs1b = *reinterpret_cast<const bf16x8*>(&Vh[(long)((k0) + 32 + sr) * LDK + sc]); KLOAD(ks0b, ks1b, k0); } while (0)
; __device__ __forceinline__ void finishSM(f32x16& p0, f32x16& p1, float alpha, float& l_reg, bf16x8& pa0, bf16x8& pa1, bf16x8& pa2, bf16x8& pa3) {
; #pragma unroll
;   for (int r = 0; r < 16; ++r) p1[r] = __builtin_amdgcn_exp2f(p1[r]);
;   float ps = 0;
; #pragma unroll
;   for (int r = 0; r < 16; ++r) ps += p0[r];
; #pragma unroll
;   for (int r = 0; r < 16; ++r) ps += p1[r];
;   { auto rr = __builtin_amdgcn_permlane32_swap(__float_as_uint(ps), __float_as_uint(ps), false, false);
;     ps = __uint_as_float(rr[0]) + __uint_as_float(rr[1]); }
;   l_reg = l_reg * alpha + ps;
;     ...
;   PK4(p0, 0, pa0); PK4(p0, 8, pa1); PK4(p1, 0, pa2); PK4(p1, 8, pa3);
; template <int ND0, int LDQ, int LDK, int LDO> ...
;     ...
;     SBAR(); qkt<ND0>(pB0, pB1, Kq1, qr, r32, hi);
;     finishSM(pA0, pA1, alA, l_reg, pa0, pa1, pa2, pa3); SBAR();
;     SLOAD_B((j + 2) * KVBLK); SBAR();
.LBB0_214:
	ds_read_b128 v[202:205], v198 offset:49152
	ds_read_b128 v[208:211], v198 offset:57344
	v_exp_f32_e32 v150, v64
	v_add_f32_e32 v64, 0, v176
	s_waitcnt lgkmcnt(3)
	v_mfma_f32_32x32x16_bf16 v[96:111], v[80:83], v[126:129], 0
	v_add_f32_e32 v64, v206, v64
	v_add_f32_e32 v64, v174, v64
	v_add_f32_e32 v64, v177, v64
	v_add_f32_e32 v64, v152, v64
	v_add_f32_e32 v64, v175, v64
	v_add_f32_e32 v64, v151, v64
	v_add_f32_e32 v64, v153, v64
	s_waitcnt lgkmcnt(2)
	v_mfma_f32_32x32x16_bf16 v[80:95], v[84:87], v[126:129], 0
	v_add_f32_e32 v64, v147, v64
	v_add_f32_e32 v64, v149, v64
	v_add_f32_e32 v64, v145, v64
	v_add_f32_e32 v64, v148, v64
	v_add_f32_e32 v64, v143, v64
	v_add_f32_e32 v64, v146, v64
	v_add_f32_e32 v64, v142, v64
	s_waitcnt lgkmcnt(1)
	v_mfma_f32_32x32x16_bf16 v[96:111], v[202:205], v[122:125], v[96:111]
	v_add_f32_e32 v64, v144, v64
	v_exp_f32_e32 v207, v68
	v_add_f32_e32 v64, v150, v64
	v_exp_f32_e32 v212, v73
	v_exp_f32_e32 v213, v74
	v_exp_f32_e32 v214, v75
	v_exp_f32_e32 v215, v76
	s_waitcnt lgkmcnt(0)
	v_mfma_f32_32x32x16_bf16 v[80:95], v[208:211], v[122:125], v[80:95]
	ds_read_b128 v[202:205], v199 offset:49152
	ds_read_b128 v[208:211], v199 offset:57344
	v_exp_f32_e32 v216, v77
	v_exp_f32_e32 v217, v78
	v_exp_f32_e32 v79, v79
	s_waitcnt lgkmcnt(1)
	v_mfma_f32_32x32x16_bf16 v[96:111], v[202:205], v[118:121], v[96:111]
	s_waitcnt lgkmcnt(0)
	v_mfma_f32_32x32x16_bf16 v[80:95], v[208:211], v[118:121], v[80:95]
	ds_read_b128 v[202:205], v196 offset:49152
	ds_read_b128 v[208:211], v196 offset:57344
	s_waitcnt lgkmcnt(1)
	v_mfma_f32_32x32x16_bf16 v[96:111], v[202:205], v[114:117], v[96:111]
	v_exp_f32_e32 v203, v65
	v_exp_f32_e32 v204, v66
	v_exp_f32_e32 v205, v67
	v_add_f32_e32 v64, v203, v64
	v_add_f32_e32 v64, v204, v64
	v_add_f32_e32 v64, v205, v64
	s_waitcnt lgkmcnt(0)
	v_mfma_f32_32x32x16_bf16 v[80:95], v[208:211], v[114:117], v[80:95]
	v_exp_f32_e32 v208, v69
	v_exp_f32_e32 v209, v70
	v_exp_f32_e32 v210, v71
	v_exp_f32_e32 v211, v72
	v_add_f32_e32 v64, v207, v64
	v_add_f32_e32 v64, v208, v64
	v_add_f32_e32 v64, v209, v64
	v_add_f32_e32 v64, v210, v64
	v_add_f32_e32 v64, v211, v64
	v_add_f32_e32 v64, v212, v64
	v_add_f32_e32 v64, v213, v64
	v_add_f32_e32 v64, v214, v64
	v_add_f32_e32 v64, v215, v64
	v_add_f32_e32 v64, v216, v64
	v_add_f32_e32 v64, v217, v64
	v_add_f32_e32 v201, v79, v64
	v_mov_b32_e32 v202, v201
	s_nop 1
	v_permlane32_swap_b32_e32 v201, v202
	v_cvt_pk_bf16_f32 v64, v176, v206
	v_cvt_pk_bf16_f32 v65, v174, v177
	v_cvt_pk_bf16_f32 v66, v152, v175
	v_cvt_pk_bf16_f32 v67, v151, v153
	v_cvt_pk_bf16_f32 v68, v147, v149
	v_cvt_pk_bf16_f32 v69, v145, v148
	v_cvt_pk_bf16_f32 v70, v143, v146
	v_cvt_pk_bf16_f32 v71, v142, v144
	v_cvt_pk_bf16_f32 v72, v150, v203
	v_cvt_pk_bf16_f32 v73, v204, v205
	v_cvt_pk_bf16_f32 v74, v207, v208
	v_cvt_pk_bf16_f32 v75, v209, v210
	v_cvt_pk_bf16_f32 v76, v211, v212
	v_cvt_pk_bf16_f32 v77, v213, v214
	v_cvt_pk_bf16_f32 v78, v215, v216
	v_cvt_pk_bf16_f32 v79, v217, v79
	s_nop 0
	v_permlane32_swap_b32_e32 v64, v66
	v_permlane32_swap_b32_e32 v65, v67
	v_permlane32_swap_b32_e32 v68, v70
	v_permlane32_swap_b32_e32 v69, v71
	v_permlane32_swap_b32_e32 v72, v74
	v_permlane32_swap_b32_e32 v73, v75
	v_permlane32_swap_b32_e32 v76, v78
	v_permlane32_swap_b32_e32 v77, v79
	v_lshl_add_u64 v[174:175], v[172:173], 0, s[34:35]
	s_mov_b32 s18, 0x13221000
	v_add_co_u32_e32 v142, vcc, s18, v174
	s_mov_b32 s18, 0x13251000
	s_nop 0
	v_addc_co_u32_e32 v143, vcc, 0, v175, vcc
	v_add_co_u32_e32 v146, vcc, s18, v174
	v_lshl_add_u64 v[176:177], v[170:171], 0, s[34:35]
	s_nop 0
	v_addc_co_u32_e32 v147, vcc, 0, v175, vcc
	s_mov_b32 s18, 0x13220000
	v_add_co_u32_e32 v150, vcc, s18, v176
	global_load_dwordx4 v[142:145], v[142:143], off
	s_nop 0
	global_load_dwordx4 v[146:149], v[146:147], off
	v_addc_co_u32_e32 v151, vcc, 0, v177, vcc
	global_load_dwordx4 v[150:153], v[150:151], off offset:2048
	v_cmp_neq_f32_e32 vcc, 0, v191
	ds_read_b64_tr_b16 v[204:205], v192 offset:0
	ds_read_b64_tr_b16 v[206:207], v192 offset:0x800
	ds_read_b64_tr_b16 v[208:209], v192 offset:0x1000
	ds_read_b64_tr_b16 v[210:211], v192 offset:0x1800
	ds_read_b64_tr_b16 v[212:213], v192 offset:0x2000
	ds_read_b64_tr_b16 v[214:215], v192 offset:0x2800
	ds_read_b64_tr_b16 v[216:217], v192 offset:0x3000
	ds_read_b64_tr_b16 v[218:219], v192 offset:0x3800
	s_cbranch_vccnz .LBB0_230
; #define SBAR() __builtin_amdgcn_sched_barrier(0)
; __device__ __forceinline__ void partialSM_pre(f32x16& p0, f32x16& p1, float& m_ref, float& alpha, const float thr2) {
;     ...
;   float pmax = p0[0];
; #pragma unroll
;   for (int r = 1; r < 16; ++r) pmax = fmaxf(pmax, p0[r]);
; #pragma unroll
;   for (int r = 0; r < 16; ++r) pmax = fmaxf(pmax, p1[r]);
;   { auto rr = __builtin_amdgcn_permlane32_swap(__float_as_uint(pmax), __float_as_uint(pmax), false, false);
;     pmax = fmaxf(__uint_as_float(rr[0]), __uint_as_float(rr[1])); }
;   if (__builtin_expect(__all(pmax <= thr2), 1)) { alpha = 1.f; }
; template <int OFF> __device__ __forceinline__ s16x4 tr_read(int vb) {
;   s16x4 r; asm volatile("ds_read_b64_tr_b16 %0, %1 offset:%2" : "=&v"(r) : "v"(vb), "i"(OFF) : "memory"); return r;
; }
; template <int D0> __device__ __forceinline__ void pv_one(f32x16& od, int vb, bf16x8 pa0, bf16x8 pa1, bf16x8 pa2, bf16x8 pa3) {
;   const s16x4 l0 = tr_read<v_rd_off(D0, 0, 0)>(vb), h0 = tr_read<v_rd_off(D0, 0, 1)>(vb), l1 = tr_read<v_rd_off(D0, 1, 0)>(vb), h1 = tr_read<v_rd_off(D0, 1, 1)>(vb);
;   const s16x4 l2 = tr_read<v_rd_off(D0, 2, 0)>(vb), h2 = tr_read<v_rd_off(D0, 2, 1)>(vb), l3 = tr_read<v_rd_off(D0, 3, 0)>(vb), h3 = tr_read<v_rd_off(D0, 3, 1)>(vb);
;   asm volatile("s_waitcnt lgkmcnt(0)" ::: "memory"); SBAR();
;     ...
;   od = __builtin_amdgcn_mfma_f32_32x32x16_bf16(pa0, PK(l0, h0), od, 0, 0, 0);
;   od = __builtin_amdgcn_mfma_f32_32x32x16_bf16(pa1, PK(l1, h1), od, 0, 0, 0);
;   od = __builtin_amdgcn_mfma_f32_32x32x16_bf16(pa2, PK(l2, h2), od, 0, 0, 0);
;   od = __builtin_amdgcn_mfma_f32_32x32x16_bf16(pa3, PK(l3, h3), od, 0, 0, 0);
;     ...
; }
; __device__ __forceinline__ void pv_d0(f32x16* o, int vb, bf16x8 pa0, bf16x8 pa1, bf16x8 pa2, bf16x8 pa3) {
;   pv_one<0>(o[0], vb, pa0, pa1, pa2, pa3); pv_one<1>(o[1], vb, pa0, pa1, pa2, pa3); pv_one<2>(o[2], vb, pa0, pa1, pa2, pa3); pv_one<3>(o[3], vb, pa0, pa1, pa2, pa3);
.LBB0_215:
	v_max_f32_e32 v252, v97, v97
	v_max_f32_e32 v253, v96, v96
	v_max_f32_e32 v252, v253, v252
	v_max3_f32 v252, v252, v98, v99
	v_max3_f32 v252, v252, v100, v101
	v_max3_f32 v252, v252, v102, v103
	v_max3_f32 v252, v252, v104, v105
	v_max3_f32 v252, v252, v106, v107
	v_max3_f32 v252, v252, v108, v109
	v_max3_f32 v252, v252, v110, v111
	v_max3_f32 v252, v252, v80, v81
	v_max3_f32 v252, v252, v82, v83
	v_max3_f32 v252, v252, v84, v85
	v_max3_f32 v252, v252, v86, v87
	v_max3_f32 v252, v252, v88, v89
	v_max3_f32 v252, v252, v90, v91
	v_max3_f32 v252, v252, v92, v93
	v_max3_f32 v252, v252, v94, v95
	v_mov_b32_e32 v253, v252
	s_nop 1
	v_permlane32_swap_b32_e32 v252, v253
	v_max_f32_e32 v253, v253, v253
	v_max_f32_e32 v252, v252, v252
	v_max_f32_e32 v252, v252, v253
	s_waitcnt lgkmcnt(0)
	s_nop 0
	v_mfma_f32_32x32x16_bf16 v[0:15], v[64:67], v[204:207], v[0:15]
	ds_read_b64_tr_b16 v[204:205], v192 offset:0x200
	ds_read_b64_tr_b16 v[206:207], v192 offset:0xa00
	v_mfma_f32_32x32x16_bf16 v[0:15], v[68:71], v[208:211], v[0:15]
	ds_read_b64_tr_b16 v[208:209], v192 offset:0x1200
	ds_read_b64_tr_b16 v[210:211], v192 offset:0x1a00
	v_mfma_f32_32x32x16_bf16 v[0:15], v[72:75], v[212:215], v[0:15]
	ds_read_b64_tr_b16 v[212:213], v192 offset:0x2200
	ds_read_b64_tr_b16 v[214:215], v192 offset:0x2a00
	v_mfma_f32_32x32x16_bf16 v[0:15], v[76:79], v[216:219], v[0:15]
	ds_read_b64_tr_b16 v[216:217], v192 offset:0x3200
	ds_read_b64_tr_b16 v[218:219], v192 offset:0x3a00
	s_waitcnt lgkmcnt(0)
	v_mfma_f32_32x32x16_bf16 v[48:63], v[64:67], v[204:207], v[48:63]
	ds_read_b64_tr_b16 v[204:205], v192 offset:0x400
	ds_read_b64_tr_b16 v[206:207], v192 offset:0xc00
	v_mfma_f32_32x32x16_bf16 v[48:63], v[68:71], v[208:211], v[48:63]
	ds_read_b64_tr_b16 v[208:209], v192 offset:0x1400
	ds_read_b64_tr_b16 v[210:211], v192 offset:0x1c00
	v_mfma_f32_32x32x16_bf16 v[48:63], v[72:75], v[212:215], v[48:63]
	ds_read_b64_tr_b16 v[212:213], v192 offset:0x2400
	ds_read_b64_tr_b16 v[214:215], v192 offset:0x2c00
	v_mfma_f32_32x32x16_bf16 v[48:63], v[76:79], v[216:219], v[48:63]
	ds_read_b64_tr_b16 v[216:217], v192 offset:0x3400
	ds_read_b64_tr_b16 v[218:219], v192 offset:0x3c00
	s_waitcnt lgkmcnt(0)
	v_mfma_f32_32x32x16_bf16 v[32:47], v[64:67], v[204:207], v[32:47]
	ds_read_b64_tr_b16 v[204:205], v192 offset:0x600
	ds_read_b64_tr_b16 v[206:207], v192 offset:0xe00
	v_mfma_f32_32x32x16_bf16 v[32:47], v[68:71], v[208:211], v[32:47]
	ds_read_b64_tr_b16 v[208:209], v192 offset:0x1600
	ds_read_b64_tr_b16 v[210:211], v192 offset:0x1e00
	v_mfma_f32_32x32x16_bf16 v[32:47], v[72:75], v[212:215], v[32:47]
	ds_read_b64_tr_b16 v[212:213], v192 offset:0x2600
	ds_read_b64_tr_b16 v[214:215], v192 offset:0x2e00
	v_mfma_f32_32x32x16_bf16 v[32:47], v[76:79], v[216:219], v[32:47]
	ds_read_b64_tr_b16 v[216:217], v192 offset:0x3600
	ds_read_b64_tr_b16 v[218:219], v192 offset:0x3e00
	s_waitcnt lgkmcnt(0)
	v_mfma_f32_32x32x16_bf16 v[16:31], v[64:67], v[204:207], v[16:31]
	s_waitcnt vmcnt(3)
	ds_write_b128 v195, v[138:141] offset:32768
	v_mfma_f32_32x32x16_bf16 v[16:31], v[68:71], v[208:211], v[16:31]
	v_mfma_f32_32x32x16_bf16 v[16:31], v[72:75], v[212:215], v[16:31]
	v_mfma_f32_32x32x16_bf16 v[16:31], v[76:79], v[216:219], v[16:31]
	v_cmp_ge_f32_e32 vcc, s45, v252
	s_cmp_eq_u64 vcc, exec
	v_mov_b32_e32 v203, 1.0
	s_cbranch_scc0 .LBB0_231

; #define SBAR() __builtin_amdgcn_sched_barrier(0)
; #define SLOAD_A(k0) do { vs0a = *reinterpret_cast<const bf16x8*>(&Vh[(long)((k0) + sr) * LDK + sc]); vs1a = *reinterpret_cast<const bf16x8*>(&Vh[(long)((k0) + 32 + sr) * LDK + sc]); KLOAD(ks0a, ks1a, k0); } while (0)
; __device__ __forceinline__ void finishSM(f32x16& p0, f32x16& p1, float alpha, float& l_reg, bf16x8& pa0, bf16x8& pa1, bf16x8& pa2, bf16x8& pa3) {
; #pragma unroll
;   for (int r = 0; r < 16; ++r) p1[r] = __builtin_amdgcn_exp2f(p1[r]);
;   float ps = 0;
; #pragma unroll
;   for (int r = 0; r < 16; ++r) ps += p0[r];
; #pragma unroll
;   for (int r = 0; r < 16; ++r) ps += p1[r];
;   { auto rr = __builtin_amdgcn_permlane32_swap(__float_as_uint(ps), __float_as_uint(ps), false, false);
;     ps = __uint_as_float(rr[0]) + __uint_as_float(rr[1]); }
;   l_reg = l_reg * alpha + ps;
;     ...
;   PK4(p0, 0, pa0); PK4(p0, 8, pa1); PK4(p1, 0, pa2); PK4(p1, 8, pa3);
; template <int ND0, int LDQ, int LDK, int LDO> ...
;     ...
;     SBAR(); qkt<ND0>(pA0, pA1, Kq0, qr, r32, hi);
;     finishSM(pB0, pB1, alB, l_reg, pa0, pa1, pa2, pa3); SBAR();
;     if (j + 3 < NT) SLOAD_A((j + 3) * KVBLK); SBAR();
.LBB0_220:
	ds_read_b128 v[64:67], v197 offset:32768
	ds_read_b128 v[68:71], v197 offset:40960
	ds_read_b128 v[222:225], v198 offset:32768
	ds_read_b128 v[244:247], v198 offset:40960
	v_exp_f32_e32 v219, v96
	v_exp_f32_e32 v221, v97
	v_exp_f32_e32 v217, v98
	v_exp_f32_e32 v220, v99
	v_exp_f32_e32 v215, v100
	v_exp_f32_e32 v218, v101
	v_exp_f32_e32 v214, v102
	v_exp_f32_e32 v216, v103
	v_exp_f32_e32 v211, v104
	v_exp_f32_e32 v213, v105
	v_exp_f32_e32 v209, v106
	v_exp_f32_e32 v212, v107
	v_exp_f32_e32 v207, v108
	v_exp_f32_e32 v210, v109
	v_exp_f32_e32 v206, v110
	v_exp_f32_e32 v208, v111
	v_exp_f32_e32 v226, v84
	v_exp_f32_e32 v227, v85
	s_waitcnt lgkmcnt(3)
	v_mfma_f32_32x32x16_bf16 v[96:111], v[64:67], v[126:129], 0
	v_exp_f32_e32 v234, v86
	v_exp_f32_e32 v235, v87
	v_exp_f32_e32 v236, v88
	v_exp_f32_e32 v237, v89
	v_exp_f32_e32 v238, v90
	v_exp_f32_e32 v239, v91
	v_exp_f32_e32 v240, v92
	s_waitcnt lgkmcnt(2)
	v_mfma_f32_32x32x16_bf16 v[64:79], v[68:71], v[126:129], 0
	v_exp_f32_e32 v241, v93
	v_exp_f32_e32 v95, v95
	s_waitcnt lgkmcnt(1)
	v_mfma_f32_32x32x16_bf16 v[96:111], v[222:225], v[122:125], v[96:111]
	s_waitcnt lgkmcnt(0)
	v_mfma_f32_32x32x16_bf16 v[64:79], v[244:247], v[122:125], v[64:79]
	ds_read_b128 v[222:225], v199 offset:32768
	ds_read_b128 v[244:247], v199 offset:40960
	s_waitcnt lgkmcnt(1)
	v_mfma_f32_32x32x16_bf16 v[96:111], v[222:225], v[118:121], v[96:111]
	s_waitcnt lgkmcnt(0)
	v_mfma_f32_32x32x16_bf16 v[64:79], v[244:247], v[118:121], v[64:79]
	ds_read_b128 v[222:225], v196 offset:32768
	ds_read_b128 v[244:247], v196 offset:40960
	s_waitcnt lgkmcnt(1)
	v_mfma_f32_32x32x16_bf16 v[96:111], v[222:225], v[114:117], v[96:111]
	v_exp_f32_e32 v222, v80
	v_add_f32_e32 v80, 0, v219
	v_add_f32_e32 v80, v221, v80
	v_add_f32_e32 v80, v217, v80
	v_add_f32_e32 v80, v220, v80
	v_add_f32_e32 v80, v215, v80
	v_add_f32_e32 v80, v218, v80
	v_add_f32_e32 v80, v214, v80
	v_add_f32_e32 v80, v216, v80
	v_add_f32_e32 v80, v211, v80
	v_add_f32_e32 v80, v213, v80
	v_add_f32_e32 v80, v209, v80
	v_add_f32_e32 v80, v212, v80
	v_add_f32_e32 v80, v207, v80
	v_exp_f32_e32 v223, v81
	v_add_f32_e32 v80, v210, v80
	v_exp_f32_e32 v224, v82
	v_add_f32_e32 v80, v206, v80
	v_exp_f32_e32 v225, v83
	v_add_f32_e32 v80, v208, v80
	v_add_f32_e32 v80, v222, v80
	v_add_f32_e32 v80, v223, v80
	v_add_f32_e32 v80, v224, v80
	v_add_f32_e32 v80, v225, v80
	v_add_f32_e32 v80, v226, v80
	v_add_f32_e32 v80, v227, v80
	v_add_f32_e32 v80, v234, v80
	v_add_f32_e32 v80, v235, v80
	v_add_f32_e32 v80, v236, v80
	v_add_f32_e32 v80, v237, v80
	s_waitcnt lgkmcnt(0)
	v_mfma_f32_32x32x16_bf16 v[64:79], v[244:247], v[114:117], v[64:79]
	v_exp_f32_e32 v244, v94
	v_add_f32_e32 v80, v238, v80
	v_add_f32_e32 v80, v239, v80
	v_add_f32_e32 v80, v240, v80
	v_add_f32_e32 v80, v241, v80
	v_add_f32_e32 v80, v244, v80
	v_add_f32_e32 v204, v95, v80
	v_mov_b32_e32 v205, v204
	v_cvt_pk_bf16_f32 v80, v219, v221
	v_cvt_pk_bf16_f32 v81, v217, v220
	v_cvt_pk_bf16_f32 v82, v215, v218
	v_cvt_pk_bf16_f32 v83, v214, v216
	v_cvt_pk_bf16_f32 v84, v211, v213
	v_cvt_pk_bf16_f32 v85, v209, v212
	v_cvt_pk_bf16_f32 v86, v207, v210
	v_cvt_pk_bf16_f32 v87, v206, v208
	v_cvt_pk_bf16_f32 v88, v222, v223
	v_cvt_pk_bf16_f32 v89, v224, v225
	v_cvt_pk_bf16_f32 v90, v226, v227
	v_cvt_pk_bf16_f32 v91, v234, v235
	v_cvt_pk_bf16_f32 v92, v236, v237
	v_cvt_pk_bf16_f32 v93, v238, v239
	v_cvt_pk_bf16_f32 v94, v240, v241
	v_cvt_pk_bf16_f32 v95, v244, v95
	s_nop 1
	v_permlane32_swap_b32_e32 v204, v205
	v_permlane32_swap_b32_e32 v80, v82
	v_permlane32_swap_b32_e32 v81, v83
	v_permlane32_swap_b32_e32 v84, v86
	v_permlane32_swap_b32_e32 v85, v87
	v_permlane32_swap_b32_e32 v88, v90
	v_permlane32_swap_b32_e32 v89, v91
	v_permlane32_swap_b32_e32 v92, v94
	v_permlane32_swap_b32_e32 v93, v95
	s_cmp_ge_u32 s40, s39
	s_cselect_b64 s[18:19], -1, 0
	s_and_b64 vcc, exec, s[18:19]
	s_cbranch_vccnz .Ldiff_pf_skip
	v_add_co_u32_e32 v130, vcc, 0x13281000, v174
	s_nop 1
	v_addc_co_u32_e32 v131, vcc, 0, v175, vcc
	v_add_co_u32_e32 v134, vcc, 0x132b1000, v174
	s_nop 1
	v_addc_co_u32_e32 v135, vcc, 0, v175, vcc
	v_add_co_u32_e32 v138, vcc, 0x13280000, v176
	global_load_dwordx4 v[130:133], v[130:131], off
	s_nop 0
	global_load_dwordx4 v[134:137], v[134:135], off
	v_addc_co_u32_e32 v139, vcc, 0, v177, vcc
	global_load_dwordx4 v[138:141], v[138:139], off offset:2048
; #define SBAR() __builtin_amdgcn_sched_barrier(0)
; __device__ __forceinline__ void partialSM_pre(f32x16& p0, f32x16& p1, float& m_ref, float& alpha, const float thr2) {
;     ...
;   float pmax = p0[0];
; #pragma unroll
;   for (int r = 1; r < 16; ++r) pmax = fmaxf(pmax, p0[r]);
; #pragma unroll
;   for (int r = 0; r < 16; ++r) pmax = fmaxf(pmax, p1[r]);
;   { auto rr = __builtin_amdgcn_permlane32_swap(__float_as_uint(pmax), __float_as_uint(pmax), false, false);
;     pmax = fmaxf(__uint_as_float(rr[0]), __uint_as_float(rr[1])); }
;   if (__builtin_expect(__all(pmax <= thr2), 1)) { alpha = 1.f; }
; template <int OFF> __device__ __forceinline__ s16x4 tr_read(int vb) {
;   s16x4 r; asm volatile("ds_read_b64_tr_b16 %0, %1 offset:%2" : "=&v"(r) : "v"(vb), "i"(OFF) : "memory"); return r;
; }
; template <int D0> __device__ __forceinline__ void pv_one(f32x16& od, int vb, bf16x8 pa0, bf16x8 pa1, bf16x8 pa2, bf16x8 pa3) {
;   const s16x4 l0 = tr_read<v_rd_off(D0, 0, 0)>(vb), h0 = tr_read<v_rd_off(D0, 0, 1)>(vb), l1 = tr_read<v_rd_off(D0, 1, 0)>(vb), h1 = tr_read<v_rd_off(D0, 1, 1)>(vb);
;   const s16x4 l2 = tr_read<v_rd_off(D0, 2, 0)>(vb), h2 = tr_read<v_rd_off(D0, 2, 1)>(vb), l3 = tr_read<v_rd_off(D0, 3, 0)>(vb), h3 = tr_read<v_rd_off(D0, 3, 1)>(vb);
;   asm volatile("s_waitcnt lgkmcnt(0)" ::: "memory"); SBAR();
;     ...
;   od = __builtin_amdgcn_mfma_f32_32x32x16_bf16(pa0, PK(l0, h0), od, 0, 0, 0);
;   od = __builtin_amdgcn_mfma_f32_32x32x16_bf16(pa1, PK(l1, h1), od, 0, 0, 0);
;   od = __builtin_amdgcn_mfma_f32_32x32x16_bf16(pa2, PK(l2, h2), od, 0, 0, 0);
;   od = __builtin_amdgcn_mfma_f32_32x32x16_bf16(pa3, PK(l3, h3), od, 0, 0, 0);
;     ...
; }
; __device__ __forceinline__ void pv_d0(f32x16* o, int vb, bf16x8 pa0, bf16x8 pa1, bf16x8 pa2, bf16x8 pa3) {
;   pv_one<0>(o[0], vb, pa0, pa1, pa2, pa3); pv_one<1>(o[1], vb, pa0, pa1, pa2, pa3); pv_one<2>(o[2], vb, pa0, pa1, pa2, pa3); pv_one<3>(o[3], vb, pa0, pa1, pa2, pa3);
.LBB0_222:
	v_cmp_neq_f32_e32 vcc, 0, v191
	ds_read_b64_tr_b16 v[174:175], v190 offset:0
	ds_read_b64_tr_b16 v[176:177], v190 offset:0x800
	ds_read_b64_tr_b16 v[206:207], v190 offset:0x1000
	ds_read_b64_tr_b16 v[208:209], v190 offset:0x1800
	ds_read_b64_tr_b16 v[210:211], v190 offset:0x2000
	ds_read_b64_tr_b16 v[212:213], v190 offset:0x2800
	ds_read_b64_tr_b16 v[214:215], v190 offset:0x3000
	ds_read_b64_tr_b16 v[216:217], v190 offset:0x3800
	s_cbranch_vccnz .LBB0_232
.LBB0_223:
	v_max_f32_e32 v252, v97, v97
	v_max_f32_e32 v253, v96, v96
	v_max_f32_e32 v252, v253, v252
	v_max3_f32 v252, v252, v98, v99
	v_max3_f32 v252, v252, v100, v101
	v_max3_f32 v252, v252, v102, v103
	v_max3_f32 v252, v252, v104, v105
	v_max3_f32 v252, v252, v106, v107
	v_max3_f32 v252, v252, v108, v109
	v_max3_f32 v252, v252, v110, v111
	v_max3_f32 v252, v252, v64, v65
	v_max3_f32 v252, v252, v66, v67
	v_max3_f32 v252, v252, v68, v69
	v_max3_f32 v252, v252, v70, v71
	v_max3_f32 v252, v252, v72, v73
	v_max3_f32 v252, v252, v74, v75
	v_max3_f32 v252, v252, v76, v77
	v_max3_f32 v252, v252, v78, v79
	v_mov_b32_e32 v253, v252
	s_nop 1
	v_permlane32_swap_b32_e32 v252, v253
	v_max_f32_e32 v253, v253, v253
	v_max_f32_e32 v252, v252, v252
	v_max_f32_e32 v252, v252, v253
	s_waitcnt lgkmcnt(0)
	s_nop 0
	v_mfma_f32_32x32x16_bf16 v[0:15], v[80:83], v[174:177], v[0:15]
	ds_read_b64_tr_b16 v[174:175], v190 offset:0x200
	ds_read_b64_tr_b16 v[176:177], v190 offset:0xa00
	v_mfma_f32_32x32x16_bf16 v[0:15], v[84:87], v[206:209], v[0:15]
	ds_read_b64_tr_b16 v[206:207], v190 offset:0x1200
	ds_read_b64_tr_b16 v[208:209], v190 offset:0x1a00
	v_mfma_f32_32x32x16_bf16 v[0:15], v[88:91], v[210:213], v[0:15]
	ds_read_b64_tr_b16 v[210:211], v190 offset:0x2200
	ds_read_b64_tr_b16 v[212:213], v190 offset:0x2a00
	v_mfma_f32_32x32x16_bf16 v[0:15], v[92:95], v[214:217], v[0:15]
	ds_read_b64_tr_b16 v[214:215], v190 offset:0x3200
	ds_read_b64_tr_b16 v[216:217], v190 offset:0x3a00
	s_waitcnt lgkmcnt(0)
	v_mfma_f32_32x32x16_bf16 v[48:63], v[80:83], v[174:177], v[48:63]
	ds_read_b64_tr_b16 v[174:175], v190 offset:0x400
	ds_read_b64_tr_b16 v[176:177], v190 offset:0xc00
	v_mfma_f32_32x32x16_bf16 v[48:63], v[84:87], v[206:209], v[48:63]
	ds_read_b64_tr_b16 v[206:207], v190 offset:0x1400
	ds_read_b64_tr_b16 v[208:209], v190 offset:0x1c00
	v_mfma_f32_32x32x16_bf16 v[48:63], v[88:91], v[210:213], v[48:63]
	ds_read_b64_tr_b16 v[210:211], v190 offset:0x2400
	ds_read_b64_tr_b16 v[212:213], v190 offset:0x2c00
	v_mfma_f32_32x32x16_bf16 v[48:63], v[92:95], v[214:217], v[48:63]
	ds_read_b64_tr_b16 v[214:215], v190 offset:0x3400
	ds_read_b64_tr_b16 v[216:217], v190 offset:0x3c00
	s_waitcnt lgkmcnt(0)
	v_mfma_f32_32x32x16_bf16 v[32:47], v[80:83], v[174:177], v[32:47]
	ds_read_b64_tr_b16 v[174:175], v190 offset:0x600
	ds_read_b64_tr_b16 v[176:177], v190 offset:0xe00
	v_mfma_f32_32x32x16_bf16 v[32:47], v[84:87], v[206:209], v[32:47]
	ds_read_b64_tr_b16 v[206:207], v190 offset:0x1600
	ds_read_b64_tr_b16 v[208:209], v190 offset:0x1e00
	v_mfma_f32_32x32x16_bf16 v[32:47], v[88:91], v[210:213], v[32:47]
	ds_read_b64_tr_b16 v[210:211], v190 offset:0x2600
	ds_read_b64_tr_b16 v[212:213], v190 offset:0x2e00
	v_mfma_f32_32x32x16_bf16 v[32:47], v[92:95], v[214:217], v[32:47]
	ds_read_b64_tr_b16 v[214:215], v190 offset:0x3600
	ds_read_b64_tr_b16 v[216:217], v190 offset:0x3e00
	s_waitcnt lgkmcnt(0)
	v_mfma_f32_32x32x16_bf16 v[16:31], v[80:83], v[174:177], v[16:31]
	s_waitcnt vmcnt(3)
	ds_write_b128 v195, v[150:153] offset:49152
	v_mfma_f32_32x32x16_bf16 v[16:31], v[84:87], v[206:209], v[16:31]
	v_mfma_f32_32x32x16_bf16 v[16:31], v[88:91], v[210:213], v[16:31]
	v_mfma_f32_32x32x16_bf16 v[16:31], v[92:95], v[214:217], v[16:31]
	v_cmp_ge_f32_e32 vcc, s45, v252
	s_cmp_eq_u64 vcc, exec
	v_mov_b32_e32 v150, 1.0
	s_cbranch_scc0 .LBB0_233

; #define SBAR() __builtin_amdgcn_sched_barrier(0)
; #define KWRITE(b, src0, src1) do { if constexpr (ND0 == 4) { *(bf16x8*)(K_lds + (b) * SHM_K + KSWZ(kr, kcb)) = src0; } \
;     else { int kc = sc * 2; *(bf16x8*)(K_lds + (b) * SHM_K + KSWZ(sr, kc)) = src0; *(bf16x8*)(K_lds + (b) * SHM_K + KSWZ(32 + sr, kc)) = src1; } } while (0)
; #define SLOAD_A(k0) do { vs0a = *reinterpret_cast<const bf16x8*>(&Vh[(long)((k0) + sr) * LDK + sc]); vs1a = *reinterpret_cast<const bf16x8*>(&Vh[(long)((k0) + 32 + sr) * LDK + sc]); KLOAD(ks0a, ks1a, k0); } while (0)
; #define SLOAD_B(k0) do { vs0b = *reinterpret_cast<const bf16x8*>(&Vh[(long)((k0) + sr) * LDK + sc]); vs1b = *reinterpret_cast<const bf16x8*>(&Vh[(long)((k0) + 32 + sr) * LDK + sc]); KLOAD(ks0b, ks1b, k0); } while (0)
; #define VWRITE_A(b) do { *(bf16x8*)(V_lds + (b) * SHM_V + vst0) = vs0a; *(bf16x8*)(V_lds + (b) * SHM_V + vst1) = vs1a; } while (0)
; #define VWRITE_B(b) do { *(bf16x8*)(V_lds + (b) * SHM_V + vst0) = vs0b; *(bf16x8*)(V_lds + (b) * SHM_V + vst1) = vs1b; } while (0)
; #define SWAIT() do { if constexpr (ND0 == 4) asm volatile("s_waitcnt vmcnt(3)" ::: "memory"); else asm volatile("s_waitcnt vmcnt(4)" ::: "memory"); } while (0)
; #define PSM(P0, P1, MN, AL) do { if constexpr (PRE) partialSM_pre(P0, P1, m_reg, AL, 11.541560327111707f); else partialSM(P0, P1, m_reg, MN, AL, C, thr_raw); } while (0)
; __device__ __forceinline__ void finishSM(f32x16& p0, f32x16& p1, float alpha, float& l_reg, bf16x8& pa0, bf16x8& pa1, bf16x8& pa2, bf16x8& pa3) {
;     ...
;   l_reg = l_reg * alpha + ps;
; template <int ND0, int LDQ, int LDK, int LDO> ...
;     ...
;   for (int j = 1; j + 1 < NT; j += 2) {
;     SBAR(); qkt<ND0>(pB0, pB1, Kq1, qr, r32, hi);
;     finishSM(pA0, pA1, alA, l_reg, pa0, pa1, pa2, pa3); SBAR();
;     SLOAD_B((j + 2) * KVBLK); SBAR();
;     pv_d0(o, vb0, pa0, pa1, pa2, pa3); KWRITE(0, ks0a, ks1a); PSM(pB0, pB1, mnB, alB);
;     __syncthreads(); SWAIT(); VWRITE_A(0);
;     RESC(alB); __syncthreads();
;     SBAR(); qkt<ND0>(pA0, pA1, Kq0, qr, r32, hi);
;     finishSM(pB0, pB1, alB, l_reg, pa0, pa1, pa2, pa3); SBAR();
;     if (j + 3 < NT) SLOAD_A((j + 3) * KVBLK); SBAR();
;     pv_d0(o, vb0 + (int)SHM_V, pa0, pa1, pa2, pa3); KWRITE(1, ks0b, ks1b); PSM(pA0, pA1, mnA, alA);
;     __syncthreads(); SWAIT(); VWRITE_B(1);
;     RESC(alA); __syncthreads();
;   }
.LBB0_228:
	v_add_f32_e32 v80, v201, v202
	v_fmac_f32_e32 v80, v200, v189
	v_add_f32_e32 v189, v204, v205
	v_fmac_f32_e32 v189, v80, v203
	ds_read_b128 v[80:83], v197 offset:49152
	ds_read_b128 v[84:87], v197 offset:57344
	v_exp_f32_e32 v176, v96
	v_exp_f32_e32 v206, v97
	v_exp_f32_e32 v174, v98
	v_exp_f32_e32 v177, v99
	v_exp_f32_e32 v152, v100
	v_exp_f32_e32 v175, v101
	v_exp_f32_e32 v151, v102
	v_exp_f32_e32 v153, v103
	v_exp_f32_e32 v147, v104
	v_exp_f32_e32 v149, v105
	v_exp_f32_e32 v145, v106
	v_exp_f32_e32 v148, v107
	v_exp_f32_e32 v143, v108
	v_exp_f32_e32 v146, v109
	v_exp_f32_e32 v142, v110
	v_exp_f32_e32 v144, v111
	v_lshl_add_u64 v[170:171], v[170:171], 0, s[46:47]
	v_lshl_add_u64 v[172:173], v[172:173], 0, s[46:47]
	s_add_i32 s40, s40, 2
	s_and_b64 vcc, exec, s[18:19]
	s_cbranch_vccnz .LBB0_234
	v_mov_b32_e32 v200, v150
	s_branch .LBB0_214

; __device__ __forceinline__ void partialSM_pre(f32x16& p0, f32x16& p1, float& m_ref, float& alpha, const float thr2) {
;     ...
;   if (__builtin_expect(__all(pmax <= thr2), 1)) { alpha = 1.f; }
;   else { const float dl = fmaxf(pmax, 0.f); m_ref += dl; alpha = __builtin_amdgcn_exp2f(-dl);
; #pragma unroll
;     for (int r = 0; r < 16; ++r) { p0[r] -= dl; p1[r] -= dl; } }
.LBB0_231:
	v_max_f32_e32 v252, v252, v252
	v_max_f32_e32 v252, 0, v252
	v_exp_f32_e64 v203, -v252
	v_add_f32_e32 v191, v191, v252
	v_pk_add_f32 v[96:97], v[96:97], v[252:253] op_sel_hi:[1,0] neg_lo:[0,1] neg_hi:[0,1]
	v_pk_add_f32 v[98:99], v[98:99], v[252:253] op_sel_hi:[1,0] neg_lo:[0,1] neg_hi:[0,1]
	v_pk_add_f32 v[100:101], v[100:101], v[252:253] op_sel_hi:[1,0] neg_lo:[0,1] neg_hi:[0,1]
	v_pk_add_f32 v[102:103], v[102:103], v[252:253] op_sel_hi:[1,0] neg_lo:[0,1] neg_hi:[0,1]
	v_pk_add_f32 v[104:105], v[104:105], v[252:253] op_sel_hi:[1,0] neg_lo:[0,1] neg_hi:[0,1]
	v_pk_add_f32 v[106:107], v[106:107], v[252:253] op_sel_hi:[1,0] neg_lo:[0,1] neg_hi:[0,1]
	v_pk_add_f32 v[108:109], v[108:109], v[252:253] op_sel_hi:[1,0] neg_lo:[0,1] neg_hi:[0,1]
	v_pk_add_f32 v[110:111], v[110:111], v[252:253] op_sel_hi:[1,0] neg_lo:[0,1] neg_hi:[0,1]
	v_sub_f32_e32 v95, v95, v252
	v_sub_f32_e32 v94, v94, v252
	v_sub_f32_e32 v93, v93, v252
	v_sub_f32_e32 v92, v92, v252
	v_sub_f32_e32 v91, v91, v252
	v_sub_f32_e32 v90, v90, v252
	v_sub_f32_e32 v89, v89, v252
	v_sub_f32_e32 v88, v88, v252
	v_sub_f32_e32 v87, v87, v252
	v_sub_f32_e32 v86, v86, v252
	v_sub_f32_e32 v85, v85, v252
	v_sub_f32_e32 v84, v84, v252
	v_sub_f32_e32 v83, v83, v252
	v_sub_f32_e32 v82, v82, v252
	v_sub_f32_e32 v81, v81, v252
	v_sub_f32_e32 v80, v80, v252
	s_branch .LBB0_216

; __device__ __forceinline__ void partialSM_pre(f32x16& p0, f32x16& p1, float& m_ref, float& alpha, const float thr2) {
;     ...
;   if (__builtin_expect(__all(pmax <= thr2), 1)) { alpha = 1.f; }
;   else { const float dl = fmaxf(pmax, 0.f); m_ref += dl; alpha = __builtin_amdgcn_exp2f(-dl);
; #pragma unroll
;     for (int r = 0; r < 16; ++r) { p0[r] -= dl; p1[r] -= dl; } }
.LBB0_233:
	v_max_f32_e32 v252, v252, v252
	v_max_f32_e32 v252, 0, v252
	v_exp_f32_e64 v150, -v252
	v_add_f32_e32 v191, v191, v252
	v_pk_add_f32 v[96:97], v[96:97], v[252:253] op_sel_hi:[1,0] neg_lo:[0,1] neg_hi:[0,1]
	v_pk_add_f32 v[98:99], v[98:99], v[252:253] op_sel_hi:[1,0] neg_lo:[0,1] neg_hi:[0,1]
	v_pk_add_f32 v[100:101], v[100:101], v[252:253] op_sel_hi:[1,0] neg_lo:[0,1] neg_hi:[0,1]
	v_pk_add_f32 v[102:103], v[102:103], v[252:253] op_sel_hi:[1,0] neg_lo:[0,1] neg_hi:[0,1]
	v_pk_add_f32 v[104:105], v[104:105], v[252:253] op_sel_hi:[1,0] neg_lo:[0,1] neg_hi:[0,1]
	v_pk_add_f32 v[106:107], v[106:107], v[252:253] op_sel_hi:[1,0] neg_lo:[0,1] neg_hi:[0,1]
	v_pk_add_f32 v[108:109], v[108:109], v[252:253] op_sel_hi:[1,0] neg_lo:[0,1] neg_hi:[0,1]
	v_pk_add_f32 v[110:111], v[110:111], v[252:253] op_sel_hi:[1,0] neg_lo:[0,1] neg_hi:[0,1]
	v_sub_f32_e32 v79, v79, v252
	v_sub_f32_e32 v78, v78, v252
	v_sub_f32_e32 v77, v77, v252
	v_sub_f32_e32 v76, v76, v252
	v_sub_f32_e32 v75, v75, v252
	v_sub_f32_e32 v74, v74, v252
	v_sub_f32_e32 v73, v73, v252
	v_sub_f32_e32 v72, v72, v252
	v_sub_f32_e32 v71, v71, v252
	v_sub_f32_e32 v70, v70, v252
	v_sub_f32_e32 v69, v69, v252
	v_sub_f32_e32 v68, v68, v252
	v_sub_f32_e32 v67, v67, v252
	v_sub_f32_e32 v66, v66, v252
	v_sub_f32_e32 v65, v65, v252
	v_sub_f32_e32 v64, v64, v252
	s_branch .LBB0_224
; #define SBAR() __builtin_amdgcn_sched_barrier(0)
; #define PSM(P0, P1, MN, AL) do { if constexpr (PRE) partialSM_pre(P0, P1, m_reg, AL, 11.541560327111707f); else partialSM(P0, P1, m_reg, MN, AL, C, thr_raw); } while (0)
; #define RESC(a) do { if (__any((a) < 1.f)) { if (hi == 0) al_l[r32] = (a); asm volatile("s_waitcnt lgkmcnt(0)" ::: "memory"); \
;     _Pragma("unroll") for (int d = 0; d < 4; ++d) _Pragma("unroll") for (int r = 0; r < 16; ++r) o[d][r] *= al_l[crow(r, hi)]; } } while (0)
; __device__ __forceinline__ void finishSM(f32x16& p0, f32x16& p1, float alpha, float& l_reg, bf16x8& pa0, bf16x8& pa1, bf16x8& pa2, bf16x8& pa3) {
; #pragma unroll
;   for (int r = 0; r < 16; ++r) p1[r] = __builtin_amdgcn_exp2f(p1[r]);
;   float ps = 0;
; #pragma unroll
;   for (int r = 0; r < 16; ++r) ps += p0[r];
; #pragma unroll
;   for (int r = 0; r < 16; ++r) ps += p1[r];
;   { auto rr = __builtin_amdgcn_permlane32_swap(__float_as_uint(ps), __float_as_uint(ps), false, false);
;     ps = __uint_as_float(rr[0]) + __uint_as_float(rr[1]); }
;   l_reg = l_reg * alpha + ps;
;     ...
;   PK4(p0, 0, pa0); PK4(p0, 8, pa1); PK4(p1, 0, pa2); PK4(p1, 8, pa3);
; template <int ND0, int LDQ, int LDK, int LDO> ...
;     ...
;   SBAR(); qkt<ND0>(pB0, pB1, Kq1, qr, r32, hi);
;   finishSM(pA0, pA1, alA, l_reg, pa0, pa1, pa2, pa3); SBAR();
;   pv_d0(o, vb0, pa0, pa1, pa2, pa3); PSM(pB0, pB1, mnB, alB);
;   __syncthreads(); RESC(alB);
.LBB0_234:
	v_exp_f32_e32 v76, v76
	v_exp_f32_e32 v77, v77
	s_waitcnt lgkmcnt(1)
	v_mfma_f32_32x32x16_bf16 v[96:111], v[80:83], v[126:129], 0
	s_waitcnt lgkmcnt(0)
	v_mfma_f32_32x32x16_bf16 v[80:95], v[84:87], v[126:129], 0
	ds_read_b128 v[126:129], v198 offset:49152
	ds_read_b128 v[130:133], v198 offset:57344
	s_waitcnt lgkmcnt(1)
	v_mfma_f32_32x32x16_bf16 v[96:111], v[126:129], v[122:125], v[96:111]
	s_waitcnt lgkmcnt(0)
	v_mfma_f32_32x32x16_bf16 v[80:95], v[130:133], v[122:125], v[80:95]
	ds_read_b128 v[122:125], v199 offset:49152
	ds_read_b128 v[126:129], v199 offset:57344
	s_waitcnt lgkmcnt(1)
	v_mfma_f32_32x32x16_bf16 v[96:111], v[122:125], v[118:121], v[96:111]
	s_waitcnt lgkmcnt(0)
	v_mfma_f32_32x32x16_bf16 v[80:95], v[126:129], v[118:121], v[80:95]
	ds_read_b128 v[118:121], v196 offset:49152
	ds_read_b128 v[122:125], v196 offset:57344
	v_exp_f32_e32 v126, v78
	v_exp_f32_e32 v127, v79
	s_waitcnt lgkmcnt(1)
	v_mfma_f32_32x32x16_bf16 v[96:111], v[118:121], v[114:117], v[96:111]
	v_exp_f32_e32 v118, v68
	v_exp_f32_e32 v119, v69
	v_exp_f32_e32 v120, v70
	v_exp_f32_e32 v121, v71
	s_waitcnt lgkmcnt(0)
	v_mfma_f32_32x32x16_bf16 v[80:95], v[122:125], v[114:117], v[80:95]
	v_exp_f32_e32 v114, v64
	v_add_f32_e32 v64, 0, v176
	v_add_f32_e32 v64, v206, v64
	v_add_f32_e32 v64, v174, v64
	v_add_f32_e32 v64, v177, v64
	v_add_f32_e32 v64, v152, v64
	v_add_f32_e32 v64, v175, v64
	v_add_f32_e32 v64, v151, v64
	v_add_f32_e32 v64, v153, v64
	v_add_f32_e32 v64, v147, v64
	v_add_f32_e32 v64, v149, v64
	v_add_f32_e32 v64, v145, v64
	v_add_f32_e32 v64, v148, v64
	v_add_f32_e32 v64, v143, v64
	v_exp_f32_e32 v115, v65
	v_add_f32_e32 v64, v146, v64
	v_exp_f32_e32 v116, v66
	v_add_f32_e32 v64, v142, v64
	v_exp_f32_e32 v117, v67
	v_add_f32_e32 v64, v144, v64
	v_add_f32_e32 v64, v114, v64
	v_add_f32_e32 v64, v115, v64
	v_add_f32_e32 v64, v116, v64
	v_add_f32_e32 v64, v117, v64
	v_exp_f32_e32 v122, v72
	v_add_f32_e32 v64, v118, v64
	v_exp_f32_e32 v123, v73
	v_add_f32_e32 v64, v119, v64
	v_exp_f32_e32 v124, v74
	v_add_f32_e32 v64, v120, v64
	v_exp_f32_e32 v125, v75
	v_add_f32_e32 v64, v121, v64
	v_add_f32_e32 v64, v122, v64
	v_add_f32_e32 v64, v123, v64
	v_add_f32_e32 v64, v124, v64
	v_add_f32_e32 v64, v125, v64
	v_add_f32_e32 v64, v76, v64
	v_add_f32_e32 v64, v77, v64
	v_add_f32_e32 v64, v126, v64
	v_add_f32_e32 v78, v127, v64
	v_mov_b32_e32 v79, v78
	s_nop 1
	v_permlane32_swap_b32_e32 v78, v79
	v_cvt_pk_bf16_f32 v64, v176, v206
	v_cvt_pk_bf16_f32 v65, v174, v177
	v_cvt_pk_bf16_f32 v66, v152, v175
	v_cvt_pk_bf16_f32 v67, v151, v153
	v_cvt_pk_bf16_f32 v68, v147, v149
	v_cvt_pk_bf16_f32 v69, v145, v148
	v_cvt_pk_bf16_f32 v70, v143, v146
	v_cvt_pk_bf16_f32 v71, v142, v144
	v_cvt_pk_bf16_f32 v72, v114, v115
	v_cvt_pk_bf16_f32 v73, v116, v117
	v_cvt_pk_bf16_f32 v74, v118, v119
	v_cvt_pk_bf16_f32 v75, v120, v121
	v_cvt_pk_bf16_f32 v114, v122, v123
	v_cvt_pk_bf16_f32 v115, v124, v125
	v_cvt_pk_bf16_f32 v116, v76, v77
	v_cvt_pk_bf16_f32 v117, v126, v127
	s_nop 0
	v_permlane32_swap_b32_e32 v64, v66
	v_permlane32_swap_b32_e32 v65, v67
	v_permlane32_swap_b32_e32 v68, v70
	v_permlane32_swap_b32_e32 v69, v71
	v_permlane32_swap_b32_e32 v72, v74
	v_permlane32_swap_b32_e32 v73, v75
	v_permlane32_swap_b32_e32 v114, v116
	v_permlane32_swap_b32_e32 v115, v117
	ds_read_b64_tr_b16 v[118:119], v192 offset:0
	ds_read_b64_tr_b16 v[120:121], v192 offset:0x800
	ds_read_b64_tr_b16 v[122:123], v192 offset:0x1000
	ds_read_b64_tr_b16 v[124:125], v192 offset:0x1800
	ds_read_b64_tr_b16 v[126:127], v192 offset:0x2000
	ds_read_b64_tr_b16 v[128:129], v192 offset:0x2800
	ds_read_b64_tr_b16 v[130:131], v192 offset:0x3000
	ds_read_b64_tr_b16 v[132:133], v192 offset:0x3800
	s_waitcnt lgkmcnt(0)
	s_nop 0
	v_mfma_f32_32x32x16_bf16 v[0:15], v[64:67], v[118:121], v[0:15]
	ds_read_b64_tr_b16 v[118:119], v192 offset:0x200
	ds_read_b64_tr_b16 v[120:121], v192 offset:0xa00
	v_mfma_f32_32x32x16_bf16 v[0:15], v[68:71], v[122:125], v[0:15]
	ds_read_b64_tr_b16 v[122:123], v192 offset:0x1200
	ds_read_b64_tr_b16 v[124:125], v192 offset:0x1a00
	v_mfma_f32_32x32x16_bf16 v[0:15], v[72:75], v[126:129], v[0:15]
	ds_read_b64_tr_b16 v[126:127], v192 offset:0x2200
	ds_read_b64_tr_b16 v[128:129], v192 offset:0x2a00
	v_mfma_f32_32x32x16_bf16 v[0:15], v[114:117], v[130:133], v[0:15]
	ds_read_b64_tr_b16 v[130:131], v192 offset:0x3200
	ds_read_b64_tr_b16 v[132:133], v192 offset:0x3a00
	s_waitcnt lgkmcnt(0)
	v_mfma_f32_32x32x16_bf16 v[48:63], v[64:67], v[118:121], v[48:63]
	ds_read_b64_tr_b16 v[118:119], v192 offset:0x400
	ds_read_b64_tr_b16 v[120:121], v192 offset:0xc00
	v_mfma_f32_32x32x16_bf16 v[48:63], v[68:71], v[122:125], v[48:63]
	ds_read_b64_tr_b16 v[122:123], v192 offset:0x1400
	ds_read_b64_tr_b16 v[124:125], v192 offset:0x1c00
	v_mfma_f32_32x32x16_bf16 v[48:63], v[72:75], v[126:129], v[48:63]
	ds_read_b64_tr_b16 v[126:127], v192 offset:0x2400
	ds_read_b64_tr_b16 v[128:129], v192 offset:0x2c00
	v_mfma_f32_32x32x16_bf16 v[48:63], v[114:117], v[130:133], v[48:63]
	ds_read_b64_tr_b16 v[130:131], v192 offset:0x3400
	ds_read_b64_tr_b16 v[132:133], v192 offset:0x3c00
	s_waitcnt lgkmcnt(0)
	v_mfma_f32_32x32x16_bf16 v[32:47], v[64:67], v[118:121], v[32:47]
	ds_read_b64_tr_b16 v[118:119], v192 offset:0x600
	ds_read_b64_tr_b16 v[120:121], v192 offset:0xe00
	v_mfma_f32_32x32x16_bf16 v[32:47], v[68:71], v[122:125], v[32:47]
	ds_read_b64_tr_b16 v[122:123], v192 offset:0x1600
	ds_read_b64_tr_b16 v[124:125], v192 offset:0x1e00
	v_mfma_f32_32x32x16_bf16 v[32:47], v[72:75], v[126:129], v[32:47]
	ds_read_b64_tr_b16 v[126:127], v192 offset:0x2600
	ds_read_b64_tr_b16 v[128:129], v192 offset:0x2e00
	v_mfma_f32_32x32x16_bf16 v[32:47], v[114:117], v[130:133], v[32:47]
	ds_read_b64_tr_b16 v[130:131], v192 offset:0x3600
	ds_read_b64_tr_b16 v[132:133], v192 offset:0x3e00
	s_waitcnt lgkmcnt(0)
	v_mfma_f32_32x32x16_bf16 v[16:31], v[64:67], v[118:121], v[16:31]
	v_cmp_neq_f32_e32 vcc, 0, v191
	v_mfma_f32_32x32x16_bf16 v[16:31], v[68:71], v[122:125], v[16:31]
	v_mfma_f32_32x32x16_bf16 v[16:31], v[72:75], v[126:129], v[16:31]
	v_mfma_f32_32x32x16_bf16 v[16:31], v[114:117], v[130:133], v[16:31]
	s_cbranch_vccnz .LBB0_247
